# counted waits: residual epilogues wait per row with vmcnt(14) on the 16 hoisted loads instead of one vmcnt(0) (rows start as their data lands)
# baseline (speedup 1.0000x reference)
; __device__ __forceinline__ unsigned cvt_pk_bf16(float lo, float hi) { unsigned r; asm volatile("v_cvt_pk_bf16_f32 %0, %1, %2" : "=v"(r) : "v"(lo), "v"(hi)); return r; }
; __device__ __forceinline__ void UNPACK8(const u32x4 q, float (&f)[8]) { f[0] = bflo(q.x); f[1] = bfhi(q.x); f[2] = bflo(q.y); f[3] = bfhi(q.y); f[4] = bflo(q.z); f[5] = bfhi(q.z); f[6] = bflo(q.w); f[7] = bfhi(q.w); }
; #define EPI_FOR_ROWS() _Pragma("unroll") for (int ai = 0; ai < 2; ++ai) _Pragma("unroll") for (int m = 0; m < 4; ++m)
;     __device__ __forceinline__ void operator()(const f32x4 (&acc)[2][2][4][2], const Unit& u, int wr, int wc, int fr, int fq) const {
;         EPI_ROWCOL();
;         EPI_FOR_ROWS() {
;             const int row = row0 + ai * 128 + m * 16; float ss = 0.f;
; #pragma unroll
;             for (int bj = 0; bj < 2; ++bj) { const int col = col0 + bj * 128; const size_t off = (size_t)row * 1024 + col;
;                 const u32x4 xw = *(const u32x4*)(xb + off); float xo[8]; UNPACK8(xw, xo);
;                 const f32x4 x0 = (f32x4){xo[0], xo[1], xo[2], xo[3]} + acc[ai][bj][m][0], x1 = (f32x4){xo[4], xo[5], xo[6], xo[7]} + acc[ai][bj][m][1];
;                 ss += (x0[0] * x0[0] + x0[1] * x0[1]) + (x0[2] * x0[2] + x0[3] * x0[3]) + (x1[0] * x1[0] + x1[1] * x1[1]) + (x1[2] * x1[2] + x1[3] * x1[3]);
;                 u32x4 w; w.x = cvt_pk_bf16(x0[0], x0[1]); w.y = cvt_pk_bf16(x0[2], x0[3]); w.z = cvt_pk_bf16(x1[0], x1[1]); w.w = cvt_pk_bf16(x1[2], x1[3]);
;                 *(u32x4*)(xb + off) = w; }
;             ss += __shfl_xor(ss, 16); ss += __shfl_xor(ss, 32);
;             if (fq == 0) ssq[(size_t)row * 16 + u.pn * 4 + wc] = ss;
.LBB0_946:
	v_lshl_add_u32 v130, s65, 8, v136
	v_ashrrev_i32_e32 v131, 31, v130
	v_lshl_or_b32 v128, s64, 8, v137
	v_lshlrev_b64 v[144:145], 11, v[130:131]
	v_ashrrev_i32_e32 v129, 31, v128
	v_lshl_add_u64 v[144:145], s[22:23], 0, v[144:145]
	v_lshl_add_u64 v[148:149], v[128:129], 1, v[144:145]
	global_load_dwordx4 v[156:159], v[148:149], off
	global_load_dwordx4 v[166:169], v[148:149], off offset:256
	s_mov_b32 s38, 0x8000
	s_mov_b32 s39, 0
	v_lshl_add_u64 v[182:183], v[148:149], 0, s[38:39]
	global_load_dwordx4 v[178:181], v[182:183], off
	global_load_dwordx4 v[182:185], v[182:183], off offset:256
	s_mov_b32 s38, 0x10000
	s_mov_b32 s39, 0
	v_lshl_add_u64 v[190:191], v[148:149], 0, s[38:39]
	global_load_dwordx4 v[186:189], v[190:191], off
	global_load_dwordx4 v[190:193], v[190:191], off offset:256
	s_mov_b32 s38, 0x18000
	s_mov_b32 s39, 0
	v_lshl_add_u64 v[198:199], v[148:149], 0, s[38:39]
	global_load_dwordx4 v[194:197], v[198:199], off
	global_load_dwordx4 v[198:201], v[198:199], off offset:256
	s_mov_b32 s38, 0x40000
	s_mov_b32 s39, 0
	v_lshl_add_u64 v[214:215], v[148:149], 0, s[38:39]
	global_load_dwordx4 v[202:205], v[214:215], off
	global_load_dwordx4 v[214:217], v[214:215], off offset:256
	s_mov_b32 s38, 0x48000
	s_mov_b32 s39, 0
	v_lshl_add_u64 v[222:223], v[148:149], 0, s[38:39]
	global_load_dwordx4 v[218:221], v[222:223], off
	global_load_dwordx4 v[222:225], v[222:223], off offset:256
	s_mov_b32 s38, 0x50000
	s_mov_b32 s39, 0
	v_lshl_add_u64 v[230:231], v[148:149], 0, s[38:39]
	global_load_dwordx4 v[226:229], v[230:231], off
	global_load_dwordx4 v[230:233], v[230:231], off offset:256
	s_mov_b32 s38, 0x58000
	s_mov_b32 s39, 0
	v_lshl_add_u64 v[238:239], v[148:149], 0, s[38:39]
	global_load_dwordx4 v[234:237], v[238:239], off
	global_load_dwordx4 v[238:241], v[238:239], off offset:256
	s_waitcnt vmcnt(14)
	v_mov_b32_e32 v144, v156
	v_mov_b32_e32 v145, v157
	v_mov_b32_e32 v146, v158
	v_mov_b32_e32 v147, v159
	s_lshl_b32 s38, s64, 2
	s_ashr_i32 s39, s38, 31
	v_lshlrev_b32_e32 v150, 16, v144
	v_and_b32_e32 v151, 0xffff0000, v144
	v_lshlrev_b32_e32 v144, 16, v145
	v_and_b32_e32 v145, 0xffff0000, v145
	v_lshlrev_b32_e32 v152, 16, v146
	v_and_b32_e32 v153, 0xffff0000, v146
	v_lshlrev_b32_e32 v146, 16, v147
	v_and_b32_e32 v147, 0xffff0000, v147
	v_pk_add_f32 v[126:127], v[126:127], v[144:145]
	v_pk_add_f32 v[124:125], v[124:125], v[150:151]
	v_pk_add_f32 v[144:145], v[122:123], v[146:147]
	v_pk_add_f32 v[122:123], v[120:121], v[152:153]
	v_mul_f32_e32 v120, v125, v125
	v_mul_f32_e32 v121, v127, v127
	v_fmac_f32_e32 v120, v124, v124
	v_fmac_f32_e32 v121, v126, v126
	v_add_f32_e32 v120, v120, v121
	v_mul_f32_e32 v121, v123, v123
	v_fmac_f32_e32 v121, v122, v122
	v_add_f32_e32 v120, v121, v120
	v_mul_f32_e32 v121, v145, v145
	v_fmac_f32_e32 v121, v144, v144
	v_add_f32_e32 v143, v121, v120
	v_cvt_pk_bf16_f32 v120, v124, v125
	v_cvt_pk_bf16_f32 v121, v126, v127
	v_cvt_pk_bf16_f32 v122, v122, v123
	v_cvt_pk_bf16_f32 v123, v144, v145
	global_store_dwordx4 v[148:149], v[120:123], off
	s_nop 1
	v_mov_b32_e32 v120, v166
	v_mov_b32_e32 v121, v167
	v_mov_b32_e32 v122, v168
	v_mov_b32_e32 v123, v169
	v_lshlrev_b32_e32 v124, 16, v120
	v_and_b32_e32 v125, 0xffff0000, v120
	v_lshlrev_b32_e32 v120, 16, v121
	v_and_b32_e32 v121, 0xffff0000, v121
	v_lshlrev_b32_e32 v126, 16, v122
	v_and_b32_e32 v127, 0xffff0000, v122
	v_lshlrev_b32_e32 v122, 16, v123
	v_and_b32_e32 v123, 0xffff0000, v123
	v_pk_add_f32 v[118:119], v[118:119], v[120:121]
	v_pk_add_f32 v[116:117], v[116:117], v[124:125]
	v_pk_add_f32 v[120:121], v[114:115], v[122:123]
	v_pk_add_f32 v[114:115], v[112:113], v[126:127]
	v_mul_f32_e32 v112, v117, v117
	v_mul_f32_e32 v113, v119, v119
	v_fmac_f32_e32 v112, v116, v116
	v_fmac_f32_e32 v113, v118, v118
	v_add_f32_e32 v112, v112, v113
	v_mul_f32_e32 v113, v115, v115
	v_fmac_f32_e32 v113, v114, v114
	v_add_f32_e32 v112, v113, v112
	v_mul_f32_e32 v113, v121, v121
	v_fmac_f32_e32 v113, v120, v120
	v_add_f32_e32 v112, v113, v112
	v_add_f32_e32 v122, v143, v112
	v_cvt_pk_bf16_f32 v112, v116, v117
	v_cvt_pk_bf16_f32 v113, v118, v119
	v_cvt_pk_bf16_f32 v114, v114, v115
	v_cvt_pk_bf16_f32 v115, v120, v121
	global_store_dwordx4 v[148:149], v[112:115], off offset:256
	s_nop 1
	v_and_b32_e32 v113, 64, v207
	v_xor_b32_e32 v112, 16, v207
	v_add_u32_e32 v113, 64, v113
	v_cmp_lt_i32_e32 vcc, v112, v113
	v_xor_b32_e32 v115, 32, v207
	s_nop 0
	v_cndmask_b32_e32 v112, v207, v112, vcc
	v_lshlrev_b32_e32 v114, 2, v112
	v_mov_b32_e32 v112, v122
	v_mov_b32_e32 v154, v122
	s_nop 1
	v_permlane16_swap_b32_e32 v112, v154
	v_cmp_lt_i32_e32 vcc, v115, v113
	s_waitcnt lgkmcnt(0)
	v_add_f32_e32 v112, v112, v154
	v_cndmask_b32_e32 v113, v207, v115, vcc
	v_lshlrev_b32_e32 v115, 2, v113
	v_mov_b32_e32 v113, v112
	v_mov_b32_e32 v154, v112
	s_nop 1
	v_permlane32_swap_b32_e32 v113, v154
	s_and_saveexec_b64 s[6:7], s[8:9]
	s_cbranch_execz .LBB0_948
	v_lshlrev_b64 v[116:117], 6, v[130:131]
	v_lshl_add_u64 v[116:117], s[18:19], 0, v[116:117]
	v_lshl_add_u64 v[116:117], s[38:39], 2, v[116:117]
	s_lshl_b32 s42, s28, 2
	s_mov_b32 s43, s36
	v_lshl_add_u64 v[116:117], v[116:117], 0, s[42:43]
	s_waitcnt lgkmcnt(0)
	v_add_f32_e32 v112, v113, v154
	global_store_dword v[116:117], v112, off
; __device__ __forceinline__ unsigned cvt_pk_bf16(float lo, float hi) { unsigned r; asm volatile("v_cvt_pk_bf16_f32 %0, %1, %2" : "=v"(r) : "v"(lo), "v"(hi)); return r; }
; __device__ __forceinline__ void UNPACK8(const u32x4 q, float (&f)[8]) { f[0] = bflo(q.x); f[1] = bfhi(q.x); f[2] = bflo(q.y); f[3] = bfhi(q.y); f[4] = bflo(q.z); f[5] = bfhi(q.z); f[6] = bflo(q.w); f[7] = bfhi(q.w); }
; #define EPI_FOR_ROWS() _Pragma("unroll") for (int ai = 0; ai < 2; ++ai) _Pragma("unroll") for (int m = 0; m < 4; ++m)
;     __device__ __forceinline__ void operator()(const f32x4 (&acc)[2][2][4][2], const Unit& u, int wr, int wc, int fr, int fq) const {
;     ...
;         EPI_FOR_ROWS() {
;             const int row = row0 + ai * 128 + m * 16; float ss = 0.f;
; #pragma unroll
;             for (int bj = 0; bj < 2; ++bj) { const int col = col0 + bj * 128; const size_t off = (size_t)row * 1024 + col;
;                 const u32x4 xw = *(const u32x4*)(xb + off); float xo[8]; UNPACK8(xw, xo);
;                 const f32x4 x0 = (f32x4){xo[0], xo[1], xo[2], xo[3]} + acc[ai][bj][m][0], x1 = (f32x4){xo[4], xo[5], xo[6], xo[7]} + acc[ai][bj][m][1];
;                 ss += (x0[0] * x0[0] + x0[1] * x0[1]) + (x0[2] * x0[2] + x0[3] * x0[3]) + (x1[0] * x1[0] + x1[1] * x1[1]) + (x1[2] * x1[2] + x1[3] * x1[3]);
;                 u32x4 w; w.x = cvt_pk_bf16(x0[0], x0[1]); w.y = cvt_pk_bf16(x0[2], x0[3]); w.z = cvt_pk_bf16(x1[0], x1[1]); w.w = cvt_pk_bf16(x1[2], x1[3]);
;                 *(u32x4*)(xb + off) = w; }
;             ss += __shfl_xor(ss, 16); ss += __shfl_xor(ss, 32);
;             if (fq == 0) ssq[(size_t)row * 16 + u.pn * 4 + wc] = ss;
.LBB0_948:
	s_or_b64 exec, exec, s[6:7]
	v_or_b32_e32 v112, 16, v130
	s_waitcnt lgkmcnt(0)
	v_ashrrev_i32_e32 v113, 31, v112
	v_lshlrev_b64 v[116:117], 11, v[112:113]
	v_lshl_add_u64 v[116:117], s[22:23], 0, v[116:117]
	v_lshl_add_u64 v[120:121], v[128:129], 1, v[116:117]
	s_waitcnt vmcnt(14)
	v_mov_b32_e32 v116, v178
	v_mov_b32_e32 v117, v179
	v_mov_b32_e32 v118, v180
	v_mov_b32_e32 v119, v181
	v_lshlrev_b32_e32 v122, 16, v116
	v_and_b32_e32 v123, 0xffff0000, v116
	v_lshlrev_b32_e32 v116, 16, v117
	v_and_b32_e32 v117, 0xffff0000, v117
	v_lshlrev_b32_e32 v124, 16, v118
	v_and_b32_e32 v125, 0xffff0000, v118
	v_lshlrev_b32_e32 v118, 16, v119
	v_and_b32_e32 v119, 0xffff0000, v119
	v_pk_add_f32 v[116:117], v[110:111], v[116:117]
	v_pk_add_f32 v[122:123], v[108:109], v[122:123]
	v_pk_add_f32 v[118:119], v[106:107], v[118:119]
	v_pk_add_f32 v[124:125], v[104:105], v[124:125]
	v_cvt_pk_bf16_f32 v104, v122, v123
	v_cvt_pk_bf16_f32 v105, v116, v117
	v_mul_f32_e32 v123, v123, v123
	v_cvt_pk_bf16_f32 v106, v124, v125
	v_cvt_pk_bf16_f32 v107, v118, v119
	v_mov_b32_e32 v108, v182
	v_mov_b32_e32 v109, v183
	v_mov_b32_e32 v110, v184
	v_mov_b32_e32 v111, v185
	v_mul_f32_e32 v117, v117, v117
	v_mul_f32_e32 v125, v125, v125
	v_fmac_f32_e32 v123, v122, v122
	v_fmac_f32_e32 v117, v116, v116
	v_mul_f32_e32 v119, v119, v119
	v_fmac_f32_e32 v125, v124, v124
	v_add_f32_e32 v116, v123, v117
	v_fmac_f32_e32 v119, v118, v118
	v_add_f32_e32 v116, v125, v116
	v_add_f32_e32 v122, v119, v116
	global_store_dwordx4 v[120:121], v[104:107], off
	v_lshlrev_b32_e32 v116, 16, v108
	v_and_b32_e32 v117, 0xffff0000, v108
	v_lshlrev_b32_e32 v108, 16, v109
	v_and_b32_e32 v109, 0xffff0000, v109
	v_lshlrev_b32_e32 v118, 16, v110
	v_and_b32_e32 v119, 0xffff0000, v110
	v_lshlrev_b32_e32 v110, 16, v111
	v_and_b32_e32 v111, 0xffff0000, v111
	v_pk_add_f32 v[102:103], v[102:103], v[108:109]
	v_pk_add_f32 v[100:101], v[100:101], v[116:117]
	v_pk_add_f32 v[108:109], v[98:99], v[110:111]
	v_pk_add_f32 v[110:111], v[96:97], v[118:119]
	v_mul_f32_e32 v96, v101, v101
	v_mul_f32_e32 v97, v103, v103
	v_mul_f32_e32 v98, v111, v111
	v_fmac_f32_e32 v96, v100, v100
	v_fmac_f32_e32 v97, v102, v102
	v_mul_f32_e32 v99, v109, v109
	v_fmac_f32_e32 v98, v110, v110
	v_add_f32_e32 v96, v96, v97
	v_add_f32_e32 v96, v98, v96
	v_fmac_f32_e32 v99, v108, v108
	v_add_f32_e32 v96, v99, v96
	v_add_f32_e32 v96, v122, v96
	v_mov_b32_e32 v97, v96
	v_mov_b32_e32 v154, v96
	s_nop 1
	v_permlane16_swap_b32_e32 v97, v154
	v_cvt_pk_bf16_f32 v98, v100, v101
	v_cvt_pk_bf16_f32 v99, v102, v103
	v_cvt_pk_bf16_f32 v100, v110, v111
	v_cvt_pk_bf16_f32 v101, v108, v109
	s_waitcnt lgkmcnt(0)
	v_add_f32_e32 v96, v97, v154
	v_mov_b32_e32 v97, v96
	v_mov_b32_e32 v154, v96
	s_nop 1
	v_permlane32_swap_b32_e32 v97, v154
	global_store_dwordx4 v[120:121], v[98:101], off offset:256
	s_and_saveexec_b64 s[6:7], s[8:9]
	s_cbranch_execz .LBB0_950
	v_lshlrev_b64 v[98:99], 6, v[112:113]
	v_lshl_add_u64 v[98:99], s[18:19], 0, v[98:99]
	v_lshl_add_u64 v[98:99], s[38:39], 2, v[98:99]
	s_lshl_b32 s42, s28, 2
	s_mov_b32 s43, s36
	v_lshl_add_u64 v[98:99], v[98:99], 0, s[42:43]
	s_waitcnt lgkmcnt(0)
	v_add_f32_e32 v96, v97, v154
	global_store_dword v[98:99], v96, off
.LBB0_950:
	s_or_b64 exec, exec, s[6:7]
	v_or_b32_e32 v96, 32, v130
	s_waitcnt lgkmcnt(0)
	v_ashrrev_i32_e32 v97, 31, v96
	v_lshlrev_b64 v[98:99], 11, v[96:97]
	v_lshl_add_u64 v[98:99], s[22:23], 0, v[98:99]
	v_lshl_add_u64 v[102:103], v[128:129], 1, v[98:99]
	s_waitcnt vmcnt(14)
	v_mov_b32_e32 v98, v186
	v_mov_b32_e32 v99, v187
	v_mov_b32_e32 v100, v188
	v_mov_b32_e32 v101, v189
	v_lshlrev_b32_e32 v104, 16, v98
	v_and_b32_e32 v105, 0xffff0000, v98
	v_lshlrev_b32_e32 v98, 16, v99
	v_and_b32_e32 v99, 0xffff0000, v99
	v_lshlrev_b32_e32 v106, 16, v100
	v_and_b32_e32 v107, 0xffff0000, v100
	v_lshlrev_b32_e32 v100, 16, v101
	v_and_b32_e32 v101, 0xffff0000, v101
	v_pk_add_f32 v[98:99], v[94:95], v[98:99]
	v_pk_add_f32 v[104:105], v[92:93], v[104:105]
	v_pk_add_f32 v[100:101], v[90:91], v[100:101]
	v_pk_add_f32 v[106:107], v[88:89], v[106:107]
	v_cvt_pk_bf16_f32 v88, v104, v105
	v_cvt_pk_bf16_f32 v89, v98, v99
	v_mul_f32_e32 v105, v105, v105
	v_cvt_pk_bf16_f32 v90, v106, v107
	v_cvt_pk_bf16_f32 v91, v100, v101
	v_mov_b32_e32 v92, v190
	v_mov_b32_e32 v93, v191
	v_mov_b32_e32 v94, v192
	v_mov_b32_e32 v95, v193
	v_mul_f32_e32 v99, v99, v99
	v_mul_f32_e32 v107, v107, v107
	v_fmac_f32_e32 v105, v104, v104
	v_fmac_f32_e32 v99, v98, v98
	v_mul_f32_e32 v101, v101, v101
	v_fmac_f32_e32 v107, v106, v106
	v_add_f32_e32 v98, v105, v99
	v_fmac_f32_e32 v101, v100, v100
	v_add_f32_e32 v98, v107, v98
	v_add_f32_e32 v104, v101, v98
	global_store_dwordx4 v[102:103], v[88:91], off
	v_lshlrev_b32_e32 v98, 16, v92
	v_and_b32_e32 v99, 0xffff0000, v92
	v_lshlrev_b32_e32 v92, 16, v93
	v_and_b32_e32 v93, 0xffff0000, v93
	v_lshlrev_b32_e32 v100, 16, v94
	v_and_b32_e32 v101, 0xffff0000, v94
	v_lshlrev_b32_e32 v94, 16, v95
	v_and_b32_e32 v95, 0xffff0000, v95
	v_pk_add_f32 v[86:87], v[86:87], v[92:93]
	v_pk_add_f32 v[84:85], v[84:85], v[98:99]
	v_pk_add_f32 v[92:93], v[82:83], v[94:95]
	v_pk_add_f32 v[94:95], v[80:81], v[100:101]
	v_mul_f32_e32 v80, v85, v85
	v_mul_f32_e32 v81, v87, v87
	v_mul_f32_e32 v82, v95, v95
	v_fmac_f32_e32 v80, v84, v84
	v_fmac_f32_e32 v81, v86, v86
	v_mul_f32_e32 v83, v93, v93
	v_fmac_f32_e32 v82, v94, v94
	v_add_f32_e32 v80, v80, v81
	v_add_f32_e32 v80, v82, v80
	v_fmac_f32_e32 v83, v92, v92
	v_add_f32_e32 v80, v83, v80
	v_add_f32_e32 v80, v104, v80
	v_mov_b32_e32 v81, v80
	v_mov_b32_e32 v154, v80
	s_nop 1
	v_permlane16_swap_b32_e32 v81, v154
	v_cvt_pk_bf16_f32 v82, v84, v85
	v_cvt_pk_bf16_f32 v83, v86, v87
	v_cvt_pk_bf16_f32 v84, v94, v95
	v_cvt_pk_bf16_f32 v85, v92, v93
	s_waitcnt lgkmcnt(0)
	v_add_f32_e32 v80, v81, v154
	v_mov_b32_e32 v81, v80
	v_mov_b32_e32 v154, v80
	s_nop 1
	v_permlane32_swap_b32_e32 v81, v154
	global_store_dwordx4 v[102:103], v[82:85], off offset:256
	s_and_saveexec_b64 s[6:7], s[8:9]
	s_cbranch_execz .LBB0_952
	v_lshlrev_b64 v[82:83], 6, v[96:97]
	v_lshl_add_u64 v[82:83], s[18:19], 0, v[82:83]
	v_lshl_add_u64 v[82:83], s[38:39], 2, v[82:83]
	s_lshl_b32 s42, s28, 2
	s_mov_b32 s43, s36
	v_lshl_add_u64 v[82:83], v[82:83], 0, s[42:43]
	s_waitcnt lgkmcnt(0)
	v_add_f32_e32 v80, v81, v154
	global_store_dword v[82:83], v80, off
; __device__ __forceinline__ unsigned cvt_pk_bf16(float lo, float hi) { unsigned r; asm volatile("v_cvt_pk_bf16_f32 %0, %1, %2" : "=v"(r) : "v"(lo), "v"(hi)); return r; }
; __device__ __forceinline__ void UNPACK8(const u32x4 q, float (&f)[8]) { f[0] = bflo(q.x); f[1] = bfhi(q.x); f[2] = bflo(q.y); f[3] = bfhi(q.y); f[4] = bflo(q.z); f[5] = bfhi(q.z); f[6] = bflo(q.w); f[7] = bfhi(q.w); }
; #define EPI_FOR_ROWS() _Pragma("unroll") for (int ai = 0; ai < 2; ++ai) _Pragma("unroll") for (int m = 0; m < 4; ++m)
;     __device__ __forceinline__ void operator()(const f32x4 (&acc)[2][2][4][2], const Unit& u, int wr, int wc, int fr, int fq) const {
;     ...
;         EPI_FOR_ROWS() {
;             const int row = row0 + ai * 128 + m * 16; float ss = 0.f;
; #pragma unroll
;             for (int bj = 0; bj < 2; ++bj) { const int col = col0 + bj * 128; const size_t off = (size_t)row * 1024 + col;
;                 const u32x4 xw = *(const u32x4*)(xb + off); float xo[8]; UNPACK8(xw, xo);
;                 const f32x4 x0 = (f32x4){xo[0], xo[1], xo[2], xo[3]} + acc[ai][bj][m][0], x1 = (f32x4){xo[4], xo[5], xo[6], xo[7]} + acc[ai][bj][m][1];
;                 ss += (x0[0] * x0[0] + x0[1] * x0[1]) + (x0[2] * x0[2] + x0[3] * x0[3]) + (x1[0] * x1[0] + x1[1] * x1[1]) + (x1[2] * x1[2] + x1[3] * x1[3]);
;                 u32x4 w; w.x = cvt_pk_bf16(x0[0], x0[1]); w.y = cvt_pk_bf16(x0[2], x0[3]); w.z = cvt_pk_bf16(x1[0], x1[1]); w.w = cvt_pk_bf16(x1[2], x1[3]);
;                 *(u32x4*)(xb + off) = w; }
;             ss += __shfl_xor(ss, 16); ss += __shfl_xor(ss, 32);
;             if (fq == 0) ssq[(size_t)row * 16 + u.pn * 4 + wc] = ss;
.LBB0_952:
	s_or_b64 exec, exec, s[6:7]
	v_or_b32_e32 v80, 48, v130
	s_waitcnt lgkmcnt(0)
	v_ashrrev_i32_e32 v81, 31, v80
	v_lshlrev_b64 v[82:83], 11, v[80:81]
	v_lshl_add_u64 v[82:83], s[22:23], 0, v[82:83]
	v_lshl_add_u64 v[86:87], v[128:129], 1, v[82:83]
	s_waitcnt vmcnt(14)
	v_mov_b32_e32 v82, v194
	v_mov_b32_e32 v83, v195
	v_mov_b32_e32 v84, v196
	v_mov_b32_e32 v85, v197
	v_lshlrev_b32_e32 v88, 16, v82
	v_and_b32_e32 v89, 0xffff0000, v82
	v_lshlrev_b32_e32 v82, 16, v83
	v_and_b32_e32 v83, 0xffff0000, v83
	v_lshlrev_b32_e32 v90, 16, v84
	v_and_b32_e32 v91, 0xffff0000, v84
	v_lshlrev_b32_e32 v84, 16, v85
	v_and_b32_e32 v85, 0xffff0000, v85
	v_pk_add_f32 v[82:83], v[78:79], v[82:83]
	v_pk_add_f32 v[88:89], v[76:77], v[88:89]
	v_pk_add_f32 v[84:85], v[74:75], v[84:85]
	v_pk_add_f32 v[90:91], v[72:73], v[90:91]
	v_cvt_pk_bf16_f32 v72, v88, v89
	v_cvt_pk_bf16_f32 v73, v82, v83
	v_mul_f32_e32 v89, v89, v89
	v_cvt_pk_bf16_f32 v74, v90, v91
	v_cvt_pk_bf16_f32 v75, v84, v85
	v_mov_b32_e32 v76, v198
	v_mov_b32_e32 v77, v199
	v_mov_b32_e32 v78, v200
	v_mov_b32_e32 v79, v201
	v_mul_f32_e32 v83, v83, v83
	v_mul_f32_e32 v91, v91, v91
	v_fmac_f32_e32 v89, v88, v88
	v_fmac_f32_e32 v83, v82, v82
	v_mul_f32_e32 v85, v85, v85
	v_fmac_f32_e32 v91, v90, v90
	v_add_f32_e32 v82, v89, v83
	v_fmac_f32_e32 v85, v84, v84
	v_add_f32_e32 v82, v91, v82
	v_add_f32_e32 v88, v85, v82
	global_store_dwordx4 v[86:87], v[72:75], off
	v_lshlrev_b32_e32 v82, 16, v76
	v_and_b32_e32 v83, 0xffff0000, v76
	v_lshlrev_b32_e32 v76, 16, v77
	v_and_b32_e32 v77, 0xffff0000, v77
	v_lshlrev_b32_e32 v84, 16, v78
	v_and_b32_e32 v85, 0xffff0000, v78
	v_lshlrev_b32_e32 v78, 16, v79
	v_and_b32_e32 v79, 0xffff0000, v79
	v_pk_add_f32 v[70:71], v[70:71], v[76:77]
	v_pk_add_f32 v[68:69], v[68:69], v[82:83]
	v_pk_add_f32 v[76:77], v[66:67], v[78:79]
	v_pk_add_f32 v[78:79], v[64:65], v[84:85]
	v_mul_f32_e32 v64, v69, v69
	v_mul_f32_e32 v65, v71, v71
	v_mul_f32_e32 v66, v79, v79
	v_fmac_f32_e32 v64, v68, v68
	v_fmac_f32_e32 v65, v70, v70
	v_mul_f32_e32 v67, v77, v77
	v_fmac_f32_e32 v66, v78, v78
	v_add_f32_e32 v64, v64, v65
	v_add_f32_e32 v64, v66, v64
	v_fmac_f32_e32 v67, v76, v76
	v_add_f32_e32 v64, v67, v64
	v_add_f32_e32 v64, v88, v64
	v_mov_b32_e32 v65, v64
	v_mov_b32_e32 v154, v64
	s_nop 1
	v_permlane16_swap_b32_e32 v65, v154
	v_cvt_pk_bf16_f32 v66, v68, v69
	v_cvt_pk_bf16_f32 v67, v70, v71
	v_cvt_pk_bf16_f32 v68, v78, v79
	v_cvt_pk_bf16_f32 v69, v76, v77
	s_waitcnt lgkmcnt(0)
	v_add_f32_e32 v64, v65, v154
	v_mov_b32_e32 v65, v64
	v_mov_b32_e32 v154, v64
	s_nop 1
	v_permlane32_swap_b32_e32 v65, v154
	global_store_dwordx4 v[86:87], v[66:69], off offset:256
	s_and_saveexec_b64 s[6:7], s[8:9]
	s_cbranch_execz .LBB0_954
	v_lshlrev_b64 v[66:67], 6, v[80:81]
	v_lshl_add_u64 v[66:67], s[18:19], 0, v[66:67]
	v_lshl_add_u64 v[66:67], s[38:39], 2, v[66:67]
	s_lshl_b32 s42, s28, 2
	s_mov_b32 s43, s36
	v_lshl_add_u64 v[66:67], v[66:67], 0, s[42:43]
	s_waitcnt lgkmcnt(0)
	v_add_f32_e32 v64, v65, v154
	global_store_dword v[66:67], v64, off
.LBB0_954:
	s_or_b64 exec, exec, s[6:7]
	v_add_u32_e32 v64, 0x80, v130
	s_waitcnt lgkmcnt(0)
	v_ashrrev_i32_e32 v65, 31, v64
	v_lshlrev_b64 v[66:67], 11, v[64:65]
	v_lshl_add_u64 v[66:67], s[22:23], 0, v[66:67]
	v_lshl_add_u64 v[70:71], v[128:129], 1, v[66:67]
	s_waitcnt vmcnt(14)
	v_mov_b32_e32 v66, v202
	v_mov_b32_e32 v67, v203
	v_mov_b32_e32 v68, v204
	v_mov_b32_e32 v69, v205
	v_lshlrev_b32_e32 v72, 16, v66
	v_and_b32_e32 v73, 0xffff0000, v66
	v_lshlrev_b32_e32 v66, 16, v67
	v_and_b32_e32 v67, 0xffff0000, v67
	v_lshlrev_b32_e32 v74, 16, v68
	v_and_b32_e32 v75, 0xffff0000, v68
	v_lshlrev_b32_e32 v68, 16, v69
	v_and_b32_e32 v69, 0xffff0000, v69
	v_pk_add_f32 v[66:67], v[62:63], v[66:67]
	v_pk_add_f32 v[72:73], v[60:61], v[72:73]
	v_pk_add_f32 v[68:69], v[58:59], v[68:69]
	v_pk_add_f32 v[74:75], v[56:57], v[74:75]
	v_cvt_pk_bf16_f32 v56, v72, v73
	v_cvt_pk_bf16_f32 v57, v66, v67
	v_mul_f32_e32 v73, v73, v73
	v_cvt_pk_bf16_f32 v58, v74, v75
	v_cvt_pk_bf16_f32 v59, v68, v69
	v_mov_b32_e32 v60, v214
	v_mov_b32_e32 v61, v215
	v_mov_b32_e32 v62, v216
	v_mov_b32_e32 v63, v217
	v_mul_f32_e32 v67, v67, v67
	v_mul_f32_e32 v75, v75, v75
	v_fmac_f32_e32 v73, v72, v72
	v_fmac_f32_e32 v67, v66, v66
	v_mul_f32_e32 v69, v69, v69
	v_fmac_f32_e32 v75, v74, v74
	v_add_f32_e32 v66, v73, v67
	v_fmac_f32_e32 v69, v68, v68
	v_add_f32_e32 v66, v75, v66
	v_add_f32_e32 v72, v69, v66
	global_store_dwordx4 v[70:71], v[56:59], off
	v_lshlrev_b32_e32 v66, 16, v60
	v_and_b32_e32 v67, 0xffff0000, v60
	v_lshlrev_b32_e32 v60, 16, v61
	v_and_b32_e32 v61, 0xffff0000, v61
	v_lshlrev_b32_e32 v68, 16, v62
	v_and_b32_e32 v69, 0xffff0000, v62
	v_lshlrev_b32_e32 v62, 16, v63
	v_and_b32_e32 v63, 0xffff0000, v63
	v_pk_add_f32 v[54:55], v[54:55], v[60:61]
	v_pk_add_f32 v[52:53], v[52:53], v[66:67]
	v_pk_add_f32 v[60:61], v[50:51], v[62:63]
	v_pk_add_f32 v[62:63], v[48:49], v[68:69]
	v_mul_f32_e32 v48, v53, v53
	v_mul_f32_e32 v49, v55, v55
	v_mul_f32_e32 v50, v63, v63
	v_fmac_f32_e32 v48, v52, v52
	v_fmac_f32_e32 v49, v54, v54
	v_mul_f32_e32 v51, v61, v61
	v_fmac_f32_e32 v50, v62, v62
	v_add_f32_e32 v48, v48, v49
	v_add_f32_e32 v48, v50, v48
	v_fmac_f32_e32 v51, v60, v60
	v_add_f32_e32 v48, v51, v48
	v_add_f32_e32 v48, v72, v48
	v_mov_b32_e32 v49, v48
	v_mov_b32_e32 v154, v48
	s_nop 1
	v_permlane16_swap_b32_e32 v49, v154
	v_cvt_pk_bf16_f32 v50, v52, v53
	v_cvt_pk_bf16_f32 v51, v54, v55
	v_cvt_pk_bf16_f32 v52, v62, v63
	v_cvt_pk_bf16_f32 v53, v60, v61
	s_waitcnt lgkmcnt(0)
	v_add_f32_e32 v48, v49, v154
	v_mov_b32_e32 v49, v48
	v_mov_b32_e32 v154, v48
	s_nop 1
	v_permlane32_swap_b32_e32 v49, v154
	global_store_dwordx4 v[70:71], v[50:53], off offset:256
	s_and_saveexec_b64 s[6:7], s[8:9]
	s_cbranch_execz .LBB0_956
	v_lshlrev_b64 v[50:51], 6, v[64:65]
	v_lshl_add_u64 v[50:51], s[18:19], 0, v[50:51]
	v_lshl_add_u64 v[50:51], s[38:39], 2, v[50:51]
	s_lshl_b32 s42, s28, 2
	s_mov_b32 s43, s36
	v_lshl_add_u64 v[50:51], v[50:51], 0, s[42:43]
	s_waitcnt lgkmcnt(0)
	v_add_f32_e32 v48, v49, v154
	global_store_dword v[50:51], v48, off
; __device__ __forceinline__ unsigned cvt_pk_bf16(float lo, float hi) { unsigned r; asm volatile("v_cvt_pk_bf16_f32 %0, %1, %2" : "=v"(r) : "v"(lo), "v"(hi)); return r; }
; __device__ __forceinline__ void UNPACK8(const u32x4 q, float (&f)[8]) { f[0] = bflo(q.x); f[1] = bfhi(q.x); f[2] = bflo(q.y); f[3] = bfhi(q.y); f[4] = bflo(q.z); f[5] = bfhi(q.z); f[6] = bflo(q.w); f[7] = bfhi(q.w); }
; #define EPI_FOR_ROWS() _Pragma("unroll") for (int ai = 0; ai < 2; ++ai) _Pragma("unroll") for (int m = 0; m < 4; ++m)
;     __device__ __forceinline__ void operator()(const f32x4 (&acc)[2][2][4][2], const Unit& u, int wr, int wc, int fr, int fq) const {
;     ...
;         EPI_FOR_ROWS() {
;             const int row = row0 + ai * 128 + m * 16; float ss = 0.f;
; #pragma unroll
;             for (int bj = 0; bj < 2; ++bj) { const int col = col0 + bj * 128; const size_t off = (size_t)row * 1024 + col;
;                 const u32x4 xw = *(const u32x4*)(xb + off); float xo[8]; UNPACK8(xw, xo);
;                 const f32x4 x0 = (f32x4){xo[0], xo[1], xo[2], xo[3]} + acc[ai][bj][m][0], x1 = (f32x4){xo[4], xo[5], xo[6], xo[7]} + acc[ai][bj][m][1];
;                 ss += (x0[0] * x0[0] + x0[1] * x0[1]) + (x0[2] * x0[2] + x0[3] * x0[3]) + (x1[0] * x1[0] + x1[1] * x1[1]) + (x1[2] * x1[2] + x1[3] * x1[3]);
;                 u32x4 w; w.x = cvt_pk_bf16(x0[0], x0[1]); w.y = cvt_pk_bf16(x0[2], x0[3]); w.z = cvt_pk_bf16(x1[0], x1[1]); w.w = cvt_pk_bf16(x1[2], x1[3]);
;                 *(u32x4*)(xb + off) = w; }
;             ss += __shfl_xor(ss, 16); ss += __shfl_xor(ss, 32);
;             if (fq == 0) ssq[(size_t)row * 16 + u.pn * 4 + wc] = ss;
.LBB0_956:
	s_or_b64 exec, exec, s[6:7]
	v_add_u32_e32 v48, 0x90, v130
	s_waitcnt lgkmcnt(0)
	v_ashrrev_i32_e32 v49, 31, v48
	v_lshlrev_b64 v[50:51], 11, v[48:49]
	v_lshl_add_u64 v[50:51], s[22:23], 0, v[50:51]
	v_lshl_add_u64 v[54:55], v[128:129], 1, v[50:51]
	s_waitcnt vmcnt(14)
	v_mov_b32_e32 v50, v218
	v_mov_b32_e32 v51, v219
	v_mov_b32_e32 v52, v220
	v_mov_b32_e32 v53, v221
	v_lshlrev_b32_e32 v56, 16, v50
	v_and_b32_e32 v57, 0xffff0000, v50
	v_lshlrev_b32_e32 v50, 16, v51
	v_and_b32_e32 v51, 0xffff0000, v51
	v_lshlrev_b32_e32 v58, 16, v52
	v_and_b32_e32 v59, 0xffff0000, v52
	v_lshlrev_b32_e32 v52, 16, v53
	v_and_b32_e32 v53, 0xffff0000, v53
	v_pk_add_f32 v[50:51], v[46:47], v[50:51]
	v_pk_add_f32 v[56:57], v[44:45], v[56:57]
	v_pk_add_f32 v[52:53], v[42:43], v[52:53]
	v_pk_add_f32 v[58:59], v[40:41], v[58:59]
	v_cvt_pk_bf16_f32 v40, v56, v57
	v_cvt_pk_bf16_f32 v41, v50, v51
	v_mul_f32_e32 v57, v57, v57
	v_cvt_pk_bf16_f32 v42, v58, v59
	v_cvt_pk_bf16_f32 v43, v52, v53
	v_mov_b32_e32 v44, v222
	v_mov_b32_e32 v45, v223
	v_mov_b32_e32 v46, v224
	v_mov_b32_e32 v47, v225
	v_mul_f32_e32 v51, v51, v51
	v_mul_f32_e32 v59, v59, v59
	v_fmac_f32_e32 v57, v56, v56
	v_fmac_f32_e32 v51, v50, v50
	v_mul_f32_e32 v53, v53, v53
	v_fmac_f32_e32 v59, v58, v58
	v_add_f32_e32 v50, v57, v51
	v_fmac_f32_e32 v53, v52, v52
	v_add_f32_e32 v50, v59, v50
	v_add_f32_e32 v56, v53, v50
	global_store_dwordx4 v[54:55], v[40:43], off
	v_lshlrev_b32_e32 v50, 16, v44
	v_and_b32_e32 v51, 0xffff0000, v44
	v_lshlrev_b32_e32 v44, 16, v45
	v_and_b32_e32 v45, 0xffff0000, v45
	v_lshlrev_b32_e32 v52, 16, v46
	v_and_b32_e32 v53, 0xffff0000, v46
	v_lshlrev_b32_e32 v46, 16, v47
	v_and_b32_e32 v47, 0xffff0000, v47
	v_pk_add_f32 v[38:39], v[38:39], v[44:45]
	v_pk_add_f32 v[36:37], v[36:37], v[50:51]
	v_pk_add_f32 v[44:45], v[34:35], v[46:47]
	v_pk_add_f32 v[46:47], v[32:33], v[52:53]
	v_mul_f32_e32 v32, v37, v37
	v_mul_f32_e32 v33, v39, v39
	v_mul_f32_e32 v34, v47, v47
	v_fmac_f32_e32 v32, v36, v36
	v_fmac_f32_e32 v33, v38, v38
	v_mul_f32_e32 v35, v45, v45
	v_fmac_f32_e32 v34, v46, v46
	v_add_f32_e32 v32, v32, v33
	v_add_f32_e32 v32, v34, v32
	v_fmac_f32_e32 v35, v44, v44
	v_add_f32_e32 v32, v35, v32
	v_add_f32_e32 v32, v56, v32
	v_mov_b32_e32 v33, v32
	v_mov_b32_e32 v154, v32
	s_nop 1
	v_permlane16_swap_b32_e32 v33, v154
	v_cvt_pk_bf16_f32 v34, v36, v37
	v_cvt_pk_bf16_f32 v35, v38, v39
	v_cvt_pk_bf16_f32 v36, v46, v47
	v_cvt_pk_bf16_f32 v37, v44, v45
	s_waitcnt lgkmcnt(0)
	v_add_f32_e32 v32, v33, v154
	v_mov_b32_e32 v33, v32
	v_mov_b32_e32 v154, v32
	s_nop 1
	v_permlane32_swap_b32_e32 v33, v154
	global_store_dwordx4 v[54:55], v[34:37], off offset:256
	s_and_saveexec_b64 s[6:7], s[8:9]
	s_cbranch_execz .LBB0_958
	v_lshlrev_b64 v[34:35], 6, v[48:49]
	v_lshl_add_u64 v[34:35], s[18:19], 0, v[34:35]
	v_lshl_add_u64 v[34:35], s[38:39], 2, v[34:35]
	s_lshl_b32 s42, s28, 2
	s_mov_b32 s43, s36
	v_lshl_add_u64 v[34:35], v[34:35], 0, s[42:43]
	s_waitcnt lgkmcnt(0)
	v_add_f32_e32 v32, v33, v154
	global_store_dword v[34:35], v32, off
; __device__ __forceinline__ unsigned cvt_pk_bf16(float lo, float hi) { unsigned r; asm volatile("v_cvt_pk_bf16_f32 %0, %1, %2" : "=v"(r) : "v"(lo), "v"(hi)); return r; }
; __device__ __forceinline__ void UNPACK8(const u32x4 q, float (&f)[8]) { f[0] = bflo(q.x); f[1] = bfhi(q.x); f[2] = bflo(q.y); f[3] = bfhi(q.y); f[4] = bflo(q.z); f[5] = bfhi(q.z); f[6] = bflo(q.w); f[7] = bfhi(q.w); }
; #define EPI_FOR_ROWS() _Pragma("unroll") for (int ai = 0; ai < 2; ++ai) _Pragma("unroll") for (int m = 0; m < 4; ++m)
;     __device__ __forceinline__ void operator()(const f32x4 (&acc)[2][2][4][2], const Unit& u, int wr, int wc, int fr, int fq) const {
;     ...
;         EPI_FOR_ROWS() {
;             const int row = row0 + ai * 128 + m * 16; float ss = 0.f;
; #pragma unroll
;             for (int bj = 0; bj < 2; ++bj) { const int col = col0 + bj * 128; const size_t off = (size_t)row * 1024 + col;
;                 const u32x4 xw = *(const u32x4*)(xb + off); float xo[8]; UNPACK8(xw, xo);
;                 const f32x4 x0 = (f32x4){xo[0], xo[1], xo[2], xo[3]} + acc[ai][bj][m][0], x1 = (f32x4){xo[4], xo[5], xo[6], xo[7]} + acc[ai][bj][m][1];
;                 ss += (x0[0] * x0[0] + x0[1] * x0[1]) + (x0[2] * x0[2] + x0[3] * x0[3]) + (x1[0] * x1[0] + x1[1] * x1[1]) + (x1[2] * x1[2] + x1[3] * x1[3]);
;                 u32x4 w; w.x = cvt_pk_bf16(x0[0], x0[1]); w.y = cvt_pk_bf16(x0[2], x0[3]); w.z = cvt_pk_bf16(x1[0], x1[1]); w.w = cvt_pk_bf16(x1[2], x1[3]);
;                 *(u32x4*)(xb + off) = w; }
;             ss += __shfl_xor(ss, 16); ss += __shfl_xor(ss, 32);
;             if (fq == 0) ssq[(size_t)row * 16 + u.pn * 4 + wc] = ss;
.LBB0_958:
	s_or_b64 exec, exec, s[6:7]
	v_add_u32_e32 v32, 0xa0, v130
	s_waitcnt lgkmcnt(0)
	v_ashrrev_i32_e32 v33, 31, v32
	v_lshlrev_b64 v[34:35], 11, v[32:33]
	v_lshl_add_u64 v[34:35], s[22:23], 0, v[34:35]
	v_lshl_add_u64 v[38:39], v[128:129], 1, v[34:35]
	s_waitcnt vmcnt(14)
	v_mov_b32_e32 v34, v226
	v_mov_b32_e32 v35, v227
	v_mov_b32_e32 v36, v228
	v_mov_b32_e32 v37, v229
	v_lshlrev_b32_e32 v40, 16, v34
	v_and_b32_e32 v41, 0xffff0000, v34
	v_lshlrev_b32_e32 v34, 16, v35
	v_and_b32_e32 v35, 0xffff0000, v35
	v_lshlrev_b32_e32 v42, 16, v36
	v_and_b32_e32 v43, 0xffff0000, v36
	v_lshlrev_b32_e32 v36, 16, v37
	v_and_b32_e32 v37, 0xffff0000, v37
	v_pk_add_f32 v[34:35], v[30:31], v[34:35]
	v_pk_add_f32 v[40:41], v[28:29], v[40:41]
	v_pk_add_f32 v[36:37], v[26:27], v[36:37]
	v_pk_add_f32 v[42:43], v[24:25], v[42:43]
	v_cvt_pk_bf16_f32 v24, v40, v41
	v_cvt_pk_bf16_f32 v25, v34, v35
	v_mul_f32_e32 v41, v41, v41
	v_cvt_pk_bf16_f32 v26, v42, v43
	v_cvt_pk_bf16_f32 v27, v36, v37
	v_mov_b32_e32 v28, v230
	v_mov_b32_e32 v29, v231
	v_mov_b32_e32 v30, v232
	v_mov_b32_e32 v31, v233
	v_mul_f32_e32 v35, v35, v35
	v_mul_f32_e32 v43, v43, v43
	v_fmac_f32_e32 v41, v40, v40
	v_fmac_f32_e32 v35, v34, v34
	v_mul_f32_e32 v37, v37, v37
	v_fmac_f32_e32 v43, v42, v42
	v_add_f32_e32 v34, v41, v35
	v_fmac_f32_e32 v37, v36, v36
	v_add_f32_e32 v34, v43, v34
	v_add_f32_e32 v40, v37, v34
	global_store_dwordx4 v[38:39], v[24:27], off
	v_lshlrev_b32_e32 v34, 16, v28
	v_and_b32_e32 v35, 0xffff0000, v28
	v_lshlrev_b32_e32 v28, 16, v29
	v_and_b32_e32 v29, 0xffff0000, v29
	v_lshlrev_b32_e32 v36, 16, v30
	v_and_b32_e32 v37, 0xffff0000, v30
	v_lshlrev_b32_e32 v30, 16, v31
	v_and_b32_e32 v31, 0xffff0000, v31
	v_pk_add_f32 v[22:23], v[22:23], v[28:29]
	v_pk_add_f32 v[20:21], v[20:21], v[34:35]
	v_pk_add_f32 v[28:29], v[18:19], v[30:31]
	v_pk_add_f32 v[30:31], v[16:17], v[36:37]
	v_mul_f32_e32 v16, v21, v21
	v_mul_f32_e32 v17, v23, v23
	v_mul_f32_e32 v18, v31, v31
	v_fmac_f32_e32 v16, v20, v20
	v_fmac_f32_e32 v17, v22, v22
	v_mul_f32_e32 v19, v29, v29
	v_fmac_f32_e32 v18, v30, v30
	v_add_f32_e32 v16, v16, v17
	v_add_f32_e32 v16, v18, v16
	v_fmac_f32_e32 v19, v28, v28
	v_add_f32_e32 v16, v19, v16
	v_add_f32_e32 v16, v40, v16
	v_mov_b32_e32 v17, v16
	v_mov_b32_e32 v154, v16
	s_nop 1
	v_permlane16_swap_b32_e32 v17, v154
	v_cvt_pk_bf16_f32 v18, v20, v21
	v_cvt_pk_bf16_f32 v19, v22, v23
	v_cvt_pk_bf16_f32 v20, v30, v31
	v_cvt_pk_bf16_f32 v21, v28, v29
	s_waitcnt lgkmcnt(0)
	v_add_f32_e32 v16, v17, v154
	v_mov_b32_e32 v17, v16
	v_mov_b32_e32 v154, v16
	s_nop 1
	v_permlane32_swap_b32_e32 v17, v154
	global_store_dwordx4 v[38:39], v[18:21], off offset:256
	s_and_saveexec_b64 s[6:7], s[8:9]
	s_cbranch_execz .LBB0_960
	v_lshlrev_b64 v[18:19], 6, v[32:33]
	v_lshl_add_u64 v[18:19], s[18:19], 0, v[18:19]
	v_lshl_add_u64 v[18:19], s[38:39], 2, v[18:19]
	s_lshl_b32 s42, s28, 2
	s_mov_b32 s43, s36
	v_lshl_add_u64 v[18:19], v[18:19], 0, s[42:43]
	s_waitcnt lgkmcnt(0)
	v_add_f32_e32 v16, v17, v154
	global_store_dword v[18:19], v16, off
.LBB0_960:
	s_or_b64 exec, exec, s[6:7]
	v_add_u32_e32 v16, 0xb0, v130
	s_waitcnt lgkmcnt(0)
	v_ashrrev_i32_e32 v17, 31, v16
	v_lshlrev_b64 v[18:19], 11, v[16:17]
	v_lshl_add_u64 v[18:19], s[22:23], 0, v[18:19]
	v_lshl_add_u64 v[22:23], v[128:129], 1, v[18:19]
	s_waitcnt vmcnt(14)
	v_mov_b32_e32 v18, v234
	v_mov_b32_e32 v19, v235
	v_mov_b32_e32 v20, v236
	v_mov_b32_e32 v21, v237
	v_lshlrev_b32_e32 v24, 16, v18
	v_and_b32_e32 v25, 0xffff0000, v18
	v_lshlrev_b32_e32 v18, 16, v19
	v_and_b32_e32 v19, 0xffff0000, v19
	v_lshlrev_b32_e32 v26, 16, v20
	v_and_b32_e32 v27, 0xffff0000, v20
	v_lshlrev_b32_e32 v20, 16, v21
	v_and_b32_e32 v21, 0xffff0000, v21
	v_pk_add_f32 v[18:19], v[14:15], v[18:19]
	v_pk_add_f32 v[24:25], v[12:13], v[24:25]
	v_pk_add_f32 v[20:21], v[10:11], v[20:21]
	v_pk_add_f32 v[26:27], v[8:9], v[26:27]
	v_cvt_pk_bf16_f32 v8, v24, v25
	v_cvt_pk_bf16_f32 v9, v18, v19
	v_mul_f32_e32 v25, v25, v25
	v_cvt_pk_bf16_f32 v10, v26, v27
	v_cvt_pk_bf16_f32 v11, v20, v21
	v_mov_b32_e32 v12, v238
	v_mov_b32_e32 v13, v239
	v_mov_b32_e32 v14, v240
	v_mov_b32_e32 v15, v241
	v_mul_f32_e32 v19, v19, v19
	v_mul_f32_e32 v27, v27, v27
	v_fmac_f32_e32 v25, v24, v24
	v_fmac_f32_e32 v19, v18, v18
	v_mul_f32_e32 v21, v21, v21
	v_fmac_f32_e32 v27, v26, v26
	v_add_f32_e32 v18, v25, v19
	v_fmac_f32_e32 v21, v20, v20
	v_add_f32_e32 v18, v27, v18
	v_add_f32_e32 v24, v21, v18
	global_store_dwordx4 v[22:23], v[8:11], off
	v_lshlrev_b32_e32 v18, 16, v12
	v_and_b32_e32 v19, 0xffff0000, v12
	v_lshlrev_b32_e32 v12, 16, v13
	v_and_b32_e32 v13, 0xffff0000, v13
	v_lshlrev_b32_e32 v20, 16, v14
	v_and_b32_e32 v21, 0xffff0000, v14
	v_lshlrev_b32_e32 v14, 16, v15
	v_and_b32_e32 v15, 0xffff0000, v15
	v_pk_add_f32 v[6:7], v[6:7], v[12:13]
	v_pk_add_f32 v[4:5], v[4:5], v[18:19]
	v_pk_add_f32 v[12:13], v[2:3], v[14:15]
	v_pk_add_f32 v[14:15], v[0:1], v[20:21]
	v_mul_f32_e32 v0, v5, v5
	v_mul_f32_e32 v1, v7, v7
	v_mul_f32_e32 v2, v15, v15
	v_fmac_f32_e32 v0, v4, v4
	v_fmac_f32_e32 v1, v6, v6
	v_mul_f32_e32 v3, v13, v13
	v_fmac_f32_e32 v2, v14, v14
	v_add_f32_e32 v0, v0, v1
	v_add_f32_e32 v0, v2, v0
	v_fmac_f32_e32 v3, v12, v12
	v_add_f32_e32 v0, v3, v0
	v_add_f32_e32 v0, v24, v0
	v_mov_b32_e32 v1, v0
	v_mov_b32_e32 v154, v0
	s_nop 1
	v_permlane16_swap_b32_e32 v1, v154
	v_cvt_pk_bf16_f32 v2, v4, v5
	v_cvt_pk_bf16_f32 v3, v6, v7
	v_cvt_pk_bf16_f32 v4, v14, v15
	v_cvt_pk_bf16_f32 v5, v12, v13
	s_waitcnt lgkmcnt(0)
	v_add_f32_e32 v0, v1, v154
	v_mov_b32_e32 v1, v0
	v_mov_b32_e32 v154, v0
	s_nop 1
	v_permlane32_swap_b32_e32 v1, v154
	global_store_dwordx4 v[22:23], v[2:5], off offset:256
	s_and_saveexec_b64 s[6:7], s[8:9]
	s_cbranch_execz .LBB0_962
	v_lshlrev_b64 v[2:3], 6, v[16:17]
	v_lshl_add_u64 v[2:3], s[18:19], 0, v[2:3]
	v_lshl_add_u64 v[2:3], s[38:39], 2, v[2:3]
	s_lshl_b32 s38, s28, 2
	s_mov_b32 s39, s36
	v_lshl_add_u64 v[2:3], v[2:3], 0, s[38:39]
	s_waitcnt lgkmcnt(0)
	v_add_f32_e32 v0, v1, v154
	global_store_dword v[2:3], v0, off

; __device__ __forceinline__ unsigned cvt_pk_bf16(float lo, float hi) { unsigned r; asm volatile("v_cvt_pk_bf16_f32 %0, %1, %2" : "=v"(r) : "v"(lo), "v"(hi)); return r; }
; __device__ __forceinline__ void UNPACK8(const u32x4 q, float (&f)[8]) { f[0] = bflo(q.x); f[1] = bfhi(q.x); f[2] = bflo(q.y); f[3] = bfhi(q.y); f[4] = bflo(q.z); f[5] = bfhi(q.z); f[6] = bflo(q.w); f[7] = bfhi(q.w); }
; #define EPI_FOR_ROWS() _Pragma("unroll") for (int ai = 0; ai < 2; ++ai) _Pragma("unroll") for (int m = 0; m < 4; ++m)
;     __device__ __forceinline__ void operator()(const f32x4 (&acc)[2][2][4][2], const Unit& u, int wr, int wc, int fr, int fq) const {
;         EPI_ROWCOL();
;         EPI_FOR_ROWS() {
;             const int row = row0 + ai * 128 + m * 16; float ss = 0.f;
; #pragma unroll
;             for (int bj = 0; bj < 2; ++bj) { const int col = col0 + bj * 128; const size_t off = (size_t)row * 1024 + col;
;                 const u32x4 xw = *(const u32x4*)(xb + off); float xo[8]; UNPACK8(xw, xo);
;                 const f32x4 x0 = (f32x4){xo[0], xo[1], xo[2], xo[3]} + acc[ai][bj][m][0], x1 = (f32x4){xo[4], xo[5], xo[6], xo[7]} + acc[ai][bj][m][1];
;                 ss += (x0[0] * x0[0] + x0[1] * x0[1]) + (x0[2] * x0[2] + x0[3] * x0[3]) + (x1[0] * x1[0] + x1[1] * x1[1]) + (x1[2] * x1[2] + x1[3] * x1[3]);
;                 u32x4 w; w.x = cvt_pk_bf16(x0[0], x0[1]); w.y = cvt_pk_bf16(x0[2], x0[3]); w.z = cvt_pk_bf16(x1[0], x1[1]); w.w = cvt_pk_bf16(x1[2], x1[3]);
;                 *(u32x4*)(xb + off) = w; }
;             ss += __shfl_xor(ss, 16); ss += __shfl_xor(ss, 32);
;             if (fq == 0) ssq[(size_t)row * 16 + u.pn * 4 + wc] = ss;
.LBB0_1143:
	v_lshl_add_u32 v130, s67, 8, v136
	v_ashrrev_i32_e32 v131, 31, v130
	v_lshl_or_b32 v128, s66, 8, v137
	v_lshlrev_b64 v[144:145], 11, v[130:131]
	v_ashrrev_i32_e32 v129, 31, v128
	v_lshl_add_u64 v[144:145], s[22:23], 0, v[144:145]
	v_lshl_add_u64 v[148:149], v[128:129], 1, v[144:145]
	global_load_dwordx4 v[156:159], v[148:149], off
	global_load_dwordx4 v[166:169], v[148:149], off offset:256
	s_mov_b32 s12, 0x8000
	s_mov_b32 s13, 0
	v_lshl_add_u64 v[182:183], v[148:149], 0, s[12:13]
	global_load_dwordx4 v[178:181], v[182:183], off
	global_load_dwordx4 v[182:185], v[182:183], off offset:256
	s_mov_b32 s12, 0x10000
	s_mov_b32 s13, 0
	v_lshl_add_u64 v[190:191], v[148:149], 0, s[12:13]
	global_load_dwordx4 v[186:189], v[190:191], off
	global_load_dwordx4 v[190:193], v[190:191], off offset:256
	s_mov_b32 s12, 0x18000
	s_mov_b32 s13, 0
	v_lshl_add_u64 v[198:199], v[148:149], 0, s[12:13]
	global_load_dwordx4 v[194:197], v[198:199], off
	global_load_dwordx4 v[198:201], v[198:199], off offset:256
	s_mov_b32 s12, 0x40000
	s_mov_b32 s13, 0
	v_lshl_add_u64 v[214:215], v[148:149], 0, s[12:13]
	global_load_dwordx4 v[202:205], v[214:215], off
	global_load_dwordx4 v[214:217], v[214:215], off offset:256
	s_mov_b32 s12, 0x48000
	s_mov_b32 s13, 0
	v_lshl_add_u64 v[222:223], v[148:149], 0, s[12:13]
	global_load_dwordx4 v[218:221], v[222:223], off
	global_load_dwordx4 v[222:225], v[222:223], off offset:256
	s_mov_b32 s12, 0x50000
	s_mov_b32 s13, 0
	v_lshl_add_u64 v[230:231], v[148:149], 0, s[12:13]
	global_load_dwordx4 v[226:229], v[230:231], off
	global_load_dwordx4 v[230:233], v[230:231], off offset:256
	s_mov_b32 s12, 0x58000
	s_mov_b32 s13, 0
	v_lshl_add_u64 v[238:239], v[148:149], 0, s[12:13]
	global_load_dwordx4 v[234:237], v[238:239], off
	global_load_dwordx4 v[238:241], v[238:239], off offset:256
	s_waitcnt vmcnt(14)
	v_mov_b32_e32 v144, v156
	v_mov_b32_e32 v145, v157
	v_mov_b32_e32 v146, v158
	v_mov_b32_e32 v147, v159
	s_lshl_b32 s12, s66, 2
	s_ashr_i32 s13, s12, 31
	v_lshlrev_b32_e32 v150, 16, v144
	v_and_b32_e32 v151, 0xffff0000, v144
	v_lshlrev_b32_e32 v144, 16, v145
	v_and_b32_e32 v145, 0xffff0000, v145
	v_lshlrev_b32_e32 v152, 16, v146
	v_and_b32_e32 v153, 0xffff0000, v146
	v_lshlrev_b32_e32 v146, 16, v147
	v_and_b32_e32 v147, 0xffff0000, v147
	v_pk_add_f32 v[126:127], v[126:127], v[144:145]
	v_pk_add_f32 v[124:125], v[124:125], v[150:151]
	v_pk_add_f32 v[144:145], v[122:123], v[146:147]
	v_pk_add_f32 v[122:123], v[120:121], v[152:153]
	v_mul_f32_e32 v120, v125, v125
	v_mul_f32_e32 v121, v127, v127
	v_fmac_f32_e32 v120, v124, v124
	v_fmac_f32_e32 v121, v126, v126
	v_add_f32_e32 v120, v120, v121
	v_mul_f32_e32 v121, v123, v123
	v_fmac_f32_e32 v121, v122, v122
	v_add_f32_e32 v120, v121, v120
	v_mul_f32_e32 v121, v145, v145
	v_fmac_f32_e32 v121, v144, v144
	v_add_f32_e32 v143, v121, v120
	v_cvt_pk_bf16_f32 v120, v124, v125
	v_cvt_pk_bf16_f32 v121, v126, v127
	v_cvt_pk_bf16_f32 v122, v122, v123
	v_cvt_pk_bf16_f32 v123, v144, v145
	global_store_dwordx4 v[148:149], v[120:123], off
	s_nop 1
	v_mov_b32_e32 v120, v166
	v_mov_b32_e32 v121, v167
	v_mov_b32_e32 v122, v168
	v_mov_b32_e32 v123, v169
	v_lshlrev_b32_e32 v124, 16, v120
	v_and_b32_e32 v125, 0xffff0000, v120
	v_lshlrev_b32_e32 v120, 16, v121
	v_and_b32_e32 v121, 0xffff0000, v121
	v_lshlrev_b32_e32 v126, 16, v122
	v_and_b32_e32 v127, 0xffff0000, v122
	v_lshlrev_b32_e32 v122, 16, v123
	v_and_b32_e32 v123, 0xffff0000, v123
	v_pk_add_f32 v[118:119], v[118:119], v[120:121]
	v_pk_add_f32 v[116:117], v[116:117], v[124:125]
	v_pk_add_f32 v[120:121], v[114:115], v[122:123]
	v_pk_add_f32 v[114:115], v[112:113], v[126:127]
	v_mul_f32_e32 v112, v117, v117
	v_mul_f32_e32 v113, v119, v119
	v_fmac_f32_e32 v112, v116, v116
	v_fmac_f32_e32 v113, v118, v118
	v_add_f32_e32 v112, v112, v113
	v_mul_f32_e32 v113, v115, v115
	v_fmac_f32_e32 v113, v114, v114
	v_add_f32_e32 v112, v113, v112
	v_mul_f32_e32 v113, v121, v121
	v_fmac_f32_e32 v113, v120, v120
	v_add_f32_e32 v112, v113, v112
	v_add_f32_e32 v122, v143, v112
	v_cvt_pk_bf16_f32 v112, v116, v117
	v_cvt_pk_bf16_f32 v113, v118, v119
	v_cvt_pk_bf16_f32 v114, v114, v115
	v_cvt_pk_bf16_f32 v115, v120, v121
	global_store_dwordx4 v[148:149], v[112:115], off offset:256
	s_nop 1
	v_and_b32_e32 v113, 64, v207
	v_xor_b32_e32 v112, 16, v207
	v_add_u32_e32 v113, 64, v113
	v_cmp_lt_i32_e32 vcc, v112, v113
	v_xor_b32_e32 v115, 32, v207
	s_nop 0
	v_cndmask_b32_e32 v112, v207, v112, vcc
	v_lshlrev_b32_e32 v114, 2, v112
	v_mov_b32_e32 v112, v122
	v_mov_b32_e32 v154, v122
	s_nop 1
	v_permlane16_swap_b32_e32 v112, v154
	v_cmp_lt_i32_e32 vcc, v115, v113
	s_waitcnt lgkmcnt(0)
	v_add_f32_e32 v112, v112, v154
	v_cndmask_b32_e32 v113, v207, v115, vcc
	v_lshlrev_b32_e32 v115, 2, v113
	v_mov_b32_e32 v113, v112
	v_mov_b32_e32 v154, v112
	s_nop 1
	v_permlane32_swap_b32_e32 v113, v154
	s_and_saveexec_b64 s[14:15], s[6:7]
	s_cbranch_execz .LBB0_1145
	v_lshlrev_b64 v[116:117], 6, v[130:131]
	v_lshl_add_u64 v[116:117], s[20:21], 0, v[116:117]
	v_lshl_add_u64 v[116:117], s[12:13], 2, v[116:117]
	s_lshl_b32 s16, s28, 2
	s_mov_b32 s17, s36
	v_lshl_add_u64 v[116:117], v[116:117], 0, s[16:17]
	s_waitcnt lgkmcnt(0)
	v_add_f32_e32 v112, v113, v154
	global_store_dword v[116:117], v112, off
; __device__ __forceinline__ unsigned cvt_pk_bf16(float lo, float hi) { unsigned r; asm volatile("v_cvt_pk_bf16_f32 %0, %1, %2" : "=v"(r) : "v"(lo), "v"(hi)); return r; }
; __device__ __forceinline__ void UNPACK8(const u32x4 q, float (&f)[8]) { f[0] = bflo(q.x); f[1] = bfhi(q.x); f[2] = bflo(q.y); f[3] = bfhi(q.y); f[4] = bflo(q.z); f[5] = bfhi(q.z); f[6] = bflo(q.w); f[7] = bfhi(q.w); }
; #define EPI_FOR_ROWS() _Pragma("unroll") for (int ai = 0; ai < 2; ++ai) _Pragma("unroll") for (int m = 0; m < 4; ++m)
;     __device__ __forceinline__ void operator()(const f32x4 (&acc)[2][2][4][2], const Unit& u, int wr, int wc, int fr, int fq) const {
;     ...
;         EPI_FOR_ROWS() {
;             const int row = row0 + ai * 128 + m * 16; float ss = 0.f;
; #pragma unroll
;             for (int bj = 0; bj < 2; ++bj) { const int col = col0 + bj * 128; const size_t off = (size_t)row * 1024 + col;
;                 const u32x4 xw = *(const u32x4*)(xb + off); float xo[8]; UNPACK8(xw, xo);
;                 const f32x4 x0 = (f32x4){xo[0], xo[1], xo[2], xo[3]} + acc[ai][bj][m][0], x1 = (f32x4){xo[4], xo[5], xo[6], xo[7]} + acc[ai][bj][m][1];
;                 ss += (x0[0] * x0[0] + x0[1] * x0[1]) + (x0[2] * x0[2] + x0[3] * x0[3]) + (x1[0] * x1[0] + x1[1] * x1[1]) + (x1[2] * x1[2] + x1[3] * x1[3]);
;                 u32x4 w; w.x = cvt_pk_bf16(x0[0], x0[1]); w.y = cvt_pk_bf16(x0[2], x0[3]); w.z = cvt_pk_bf16(x1[0], x1[1]); w.w = cvt_pk_bf16(x1[2], x1[3]);
;                 *(u32x4*)(xb + off) = w; }
;             ss += __shfl_xor(ss, 16); ss += __shfl_xor(ss, 32);
;             if (fq == 0) ssq[(size_t)row * 16 + u.pn * 4 + wc] = ss;
.LBB0_1145:
	s_or_b64 exec, exec, s[14:15]
	v_or_b32_e32 v112, 16, v130
	s_waitcnt lgkmcnt(0)
	v_ashrrev_i32_e32 v113, 31, v112
	v_lshlrev_b64 v[116:117], 11, v[112:113]
	v_lshl_add_u64 v[116:117], s[22:23], 0, v[116:117]
	v_lshl_add_u64 v[120:121], v[128:129], 1, v[116:117]
	s_waitcnt vmcnt(14)
	v_mov_b32_e32 v116, v178
	v_mov_b32_e32 v117, v179
	v_mov_b32_e32 v118, v180
	v_mov_b32_e32 v119, v181
	v_lshlrev_b32_e32 v122, 16, v116
	v_and_b32_e32 v123, 0xffff0000, v116
	v_lshlrev_b32_e32 v116, 16, v117
	v_and_b32_e32 v117, 0xffff0000, v117
	v_lshlrev_b32_e32 v124, 16, v118
	v_and_b32_e32 v125, 0xffff0000, v118
	v_lshlrev_b32_e32 v118, 16, v119
	v_and_b32_e32 v119, 0xffff0000, v119
	v_pk_add_f32 v[116:117], v[110:111], v[116:117]
	v_pk_add_f32 v[122:123], v[108:109], v[122:123]
	v_pk_add_f32 v[118:119], v[106:107], v[118:119]
	v_pk_add_f32 v[124:125], v[104:105], v[124:125]
	v_cvt_pk_bf16_f32 v104, v122, v123
	v_cvt_pk_bf16_f32 v105, v116, v117
	v_mul_f32_e32 v123, v123, v123
	v_cvt_pk_bf16_f32 v106, v124, v125
	v_cvt_pk_bf16_f32 v107, v118, v119
	v_mov_b32_e32 v108, v182
	v_mov_b32_e32 v109, v183
	v_mov_b32_e32 v110, v184
	v_mov_b32_e32 v111, v185
	v_mul_f32_e32 v117, v117, v117
	v_mul_f32_e32 v125, v125, v125
	v_fmac_f32_e32 v123, v122, v122
	v_fmac_f32_e32 v117, v116, v116
	v_mul_f32_e32 v119, v119, v119
	v_fmac_f32_e32 v125, v124, v124
	v_add_f32_e32 v116, v123, v117
	v_fmac_f32_e32 v119, v118, v118
	v_add_f32_e32 v116, v125, v116
	v_add_f32_e32 v122, v119, v116
	global_store_dwordx4 v[120:121], v[104:107], off
	v_lshlrev_b32_e32 v116, 16, v108
	v_and_b32_e32 v117, 0xffff0000, v108
	v_lshlrev_b32_e32 v108, 16, v109
	v_and_b32_e32 v109, 0xffff0000, v109
	v_lshlrev_b32_e32 v118, 16, v110
	v_and_b32_e32 v119, 0xffff0000, v110
	v_lshlrev_b32_e32 v110, 16, v111
	v_and_b32_e32 v111, 0xffff0000, v111
	v_pk_add_f32 v[102:103], v[102:103], v[108:109]
	v_pk_add_f32 v[100:101], v[100:101], v[116:117]
	v_pk_add_f32 v[108:109], v[98:99], v[110:111]
	v_pk_add_f32 v[110:111], v[96:97], v[118:119]
	v_mul_f32_e32 v96, v101, v101
	v_mul_f32_e32 v97, v103, v103
	v_mul_f32_e32 v98, v111, v111
	v_fmac_f32_e32 v96, v100, v100
	v_fmac_f32_e32 v97, v102, v102
	v_mul_f32_e32 v99, v109, v109
	v_fmac_f32_e32 v98, v110, v110
	v_add_f32_e32 v96, v96, v97
	v_add_f32_e32 v96, v98, v96
	v_fmac_f32_e32 v99, v108, v108
	v_add_f32_e32 v96, v99, v96
	v_add_f32_e32 v96, v122, v96
	v_mov_b32_e32 v97, v96
	v_mov_b32_e32 v154, v96
	s_nop 1
	v_permlane16_swap_b32_e32 v97, v154
	v_cvt_pk_bf16_f32 v98, v100, v101
	v_cvt_pk_bf16_f32 v99, v102, v103
	v_cvt_pk_bf16_f32 v100, v110, v111
	v_cvt_pk_bf16_f32 v101, v108, v109
	s_waitcnt lgkmcnt(0)
	v_add_f32_e32 v96, v97, v154
	v_mov_b32_e32 v97, v96
	v_mov_b32_e32 v154, v96
	s_nop 1
	v_permlane32_swap_b32_e32 v97, v154
	global_store_dwordx4 v[120:121], v[98:101], off offset:256
	s_and_saveexec_b64 s[14:15], s[6:7]
	s_cbranch_execz .LBB0_1147
	v_lshlrev_b64 v[98:99], 6, v[112:113]
	v_lshl_add_u64 v[98:99], s[20:21], 0, v[98:99]
	v_lshl_add_u64 v[98:99], s[12:13], 2, v[98:99]
	s_lshl_b32 s16, s28, 2
	s_mov_b32 s17, s36
	v_lshl_add_u64 v[98:99], v[98:99], 0, s[16:17]
	s_waitcnt lgkmcnt(0)
	v_add_f32_e32 v96, v97, v154
	global_store_dword v[98:99], v96, off
.LBB0_1147:
	s_or_b64 exec, exec, s[14:15]
	v_or_b32_e32 v96, 32, v130
	s_waitcnt lgkmcnt(0)
	v_ashrrev_i32_e32 v97, 31, v96
	v_lshlrev_b64 v[98:99], 11, v[96:97]
	v_lshl_add_u64 v[98:99], s[22:23], 0, v[98:99]
	v_lshl_add_u64 v[102:103], v[128:129], 1, v[98:99]
	s_waitcnt vmcnt(14)
	v_mov_b32_e32 v98, v186
	v_mov_b32_e32 v99, v187
	v_mov_b32_e32 v100, v188
	v_mov_b32_e32 v101, v189
	v_lshlrev_b32_e32 v104, 16, v98
	v_and_b32_e32 v105, 0xffff0000, v98
	v_lshlrev_b32_e32 v98, 16, v99
	v_and_b32_e32 v99, 0xffff0000, v99
	v_lshlrev_b32_e32 v106, 16, v100
	v_and_b32_e32 v107, 0xffff0000, v100
	v_lshlrev_b32_e32 v100, 16, v101
	v_and_b32_e32 v101, 0xffff0000, v101
	v_pk_add_f32 v[98:99], v[94:95], v[98:99]
	v_pk_add_f32 v[104:105], v[92:93], v[104:105]
	v_pk_add_f32 v[100:101], v[90:91], v[100:101]
	v_pk_add_f32 v[106:107], v[88:89], v[106:107]
	v_cvt_pk_bf16_f32 v88, v104, v105
	v_cvt_pk_bf16_f32 v89, v98, v99
	v_mul_f32_e32 v105, v105, v105
	v_cvt_pk_bf16_f32 v90, v106, v107
	v_cvt_pk_bf16_f32 v91, v100, v101
	v_mov_b32_e32 v92, v190
	v_mov_b32_e32 v93, v191
	v_mov_b32_e32 v94, v192
	v_mov_b32_e32 v95, v193
	v_mul_f32_e32 v99, v99, v99
	v_mul_f32_e32 v107, v107, v107
	v_fmac_f32_e32 v105, v104, v104
	v_fmac_f32_e32 v99, v98, v98
	v_mul_f32_e32 v101, v101, v101
	v_fmac_f32_e32 v107, v106, v106
	v_add_f32_e32 v98, v105, v99
	v_fmac_f32_e32 v101, v100, v100
	v_add_f32_e32 v98, v107, v98
	v_add_f32_e32 v104, v101, v98
	global_store_dwordx4 v[102:103], v[88:91], off
	v_lshlrev_b32_e32 v98, 16, v92
	v_and_b32_e32 v99, 0xffff0000, v92
	v_lshlrev_b32_e32 v92, 16, v93
	v_and_b32_e32 v93, 0xffff0000, v93
	v_lshlrev_b32_e32 v100, 16, v94
	v_and_b32_e32 v101, 0xffff0000, v94
	v_lshlrev_b32_e32 v94, 16, v95
	v_and_b32_e32 v95, 0xffff0000, v95
	v_pk_add_f32 v[86:87], v[86:87], v[92:93]
	v_pk_add_f32 v[84:85], v[84:85], v[98:99]
	v_pk_add_f32 v[92:93], v[82:83], v[94:95]
	v_pk_add_f32 v[94:95], v[80:81], v[100:101]
	v_mul_f32_e32 v80, v85, v85
	v_mul_f32_e32 v81, v87, v87
	v_mul_f32_e32 v82, v95, v95
	v_fmac_f32_e32 v80, v84, v84
	v_fmac_f32_e32 v81, v86, v86
	v_mul_f32_e32 v83, v93, v93
	v_fmac_f32_e32 v82, v94, v94
	v_add_f32_e32 v80, v80, v81
	v_add_f32_e32 v80, v82, v80
	v_fmac_f32_e32 v83, v92, v92
	v_add_f32_e32 v80, v83, v80
	v_add_f32_e32 v80, v104, v80
	v_mov_b32_e32 v81, v80
	v_mov_b32_e32 v154, v80
	s_nop 1
	v_permlane16_swap_b32_e32 v81, v154
	v_cvt_pk_bf16_f32 v82, v84, v85
	v_cvt_pk_bf16_f32 v83, v86, v87
	v_cvt_pk_bf16_f32 v84, v94, v95
	v_cvt_pk_bf16_f32 v85, v92, v93
	s_waitcnt lgkmcnt(0)
	v_add_f32_e32 v80, v81, v154
	v_mov_b32_e32 v81, v80
	v_mov_b32_e32 v154, v80
	s_nop 1
	v_permlane32_swap_b32_e32 v81, v154
	global_store_dwordx4 v[102:103], v[82:85], off offset:256
	s_and_saveexec_b64 s[14:15], s[6:7]
	s_cbranch_execz .LBB0_1149
	v_lshlrev_b64 v[82:83], 6, v[96:97]
	v_lshl_add_u64 v[82:83], s[20:21], 0, v[82:83]
	v_lshl_add_u64 v[82:83], s[12:13], 2, v[82:83]
	s_lshl_b32 s16, s28, 2
	s_mov_b32 s17, s36
	v_lshl_add_u64 v[82:83], v[82:83], 0, s[16:17]
	s_waitcnt lgkmcnt(0)
	v_add_f32_e32 v80, v81, v154
	global_store_dword v[82:83], v80, off
; __device__ __forceinline__ unsigned cvt_pk_bf16(float lo, float hi) { unsigned r; asm volatile("v_cvt_pk_bf16_f32 %0, %1, %2" : "=v"(r) : "v"(lo), "v"(hi)); return r; }
; __device__ __forceinline__ void UNPACK8(const u32x4 q, float (&f)[8]) { f[0] = bflo(q.x); f[1] = bfhi(q.x); f[2] = bflo(q.y); f[3] = bfhi(q.y); f[4] = bflo(q.z); f[5] = bfhi(q.z); f[6] = bflo(q.w); f[7] = bfhi(q.w); }
; #define EPI_FOR_ROWS() _Pragma("unroll") for (int ai = 0; ai < 2; ++ai) _Pragma("unroll") for (int m = 0; m < 4; ++m)
;     __device__ __forceinline__ void operator()(const f32x4 (&acc)[2][2][4][2], const Unit& u, int wr, int wc, int fr, int fq) const {
;     ...
;         EPI_FOR_ROWS() {
;             const int row = row0 + ai * 128 + m * 16; float ss = 0.f;
; #pragma unroll
;             for (int bj = 0; bj < 2; ++bj) { const int col = col0 + bj * 128; const size_t off = (size_t)row * 1024 + col;
;                 const u32x4 xw = *(const u32x4*)(xb + off); float xo[8]; UNPACK8(xw, xo);
;                 const f32x4 x0 = (f32x4){xo[0], xo[1], xo[2], xo[3]} + acc[ai][bj][m][0], x1 = (f32x4){xo[4], xo[5], xo[6], xo[7]} + acc[ai][bj][m][1];
;                 ss += (x0[0] * x0[0] + x0[1] * x0[1]) + (x0[2] * x0[2] + x0[3] * x0[3]) + (x1[0] * x1[0] + x1[1] * x1[1]) + (x1[2] * x1[2] + x1[3] * x1[3]);
;                 u32x4 w; w.x = cvt_pk_bf16(x0[0], x0[1]); w.y = cvt_pk_bf16(x0[2], x0[3]); w.z = cvt_pk_bf16(x1[0], x1[1]); w.w = cvt_pk_bf16(x1[2], x1[3]);
;                 *(u32x4*)(xb + off) = w; }
;             ss += __shfl_xor(ss, 16); ss += __shfl_xor(ss, 32);
;             if (fq == 0) ssq[(size_t)row * 16 + u.pn * 4 + wc] = ss;
.LBB0_1149:
	s_or_b64 exec, exec, s[14:15]
	v_or_b32_e32 v80, 48, v130
	s_waitcnt lgkmcnt(0)
	v_ashrrev_i32_e32 v81, 31, v80
	v_lshlrev_b64 v[82:83], 11, v[80:81]
	v_lshl_add_u64 v[82:83], s[22:23], 0, v[82:83]
	v_lshl_add_u64 v[86:87], v[128:129], 1, v[82:83]
	s_waitcnt vmcnt(14)
	v_mov_b32_e32 v82, v194
	v_mov_b32_e32 v83, v195
	v_mov_b32_e32 v84, v196
	v_mov_b32_e32 v85, v197
	v_lshlrev_b32_e32 v88, 16, v82
	v_and_b32_e32 v89, 0xffff0000, v82
	v_lshlrev_b32_e32 v82, 16, v83
	v_and_b32_e32 v83, 0xffff0000, v83
	v_lshlrev_b32_e32 v90, 16, v84
	v_and_b32_e32 v91, 0xffff0000, v84
	v_lshlrev_b32_e32 v84, 16, v85
	v_and_b32_e32 v85, 0xffff0000, v85
	v_pk_add_f32 v[82:83], v[78:79], v[82:83]
	v_pk_add_f32 v[88:89], v[76:77], v[88:89]
	v_pk_add_f32 v[84:85], v[74:75], v[84:85]
	v_pk_add_f32 v[90:91], v[72:73], v[90:91]
	v_cvt_pk_bf16_f32 v72, v88, v89
	v_cvt_pk_bf16_f32 v73, v82, v83
	v_mul_f32_e32 v89, v89, v89
	v_cvt_pk_bf16_f32 v74, v90, v91
	v_cvt_pk_bf16_f32 v75, v84, v85
	v_mov_b32_e32 v76, v198
	v_mov_b32_e32 v77, v199
	v_mov_b32_e32 v78, v200
	v_mov_b32_e32 v79, v201
	v_mul_f32_e32 v83, v83, v83
	v_mul_f32_e32 v91, v91, v91
	v_fmac_f32_e32 v89, v88, v88
	v_fmac_f32_e32 v83, v82, v82
	v_mul_f32_e32 v85, v85, v85
	v_fmac_f32_e32 v91, v90, v90
	v_add_f32_e32 v82, v89, v83
	v_fmac_f32_e32 v85, v84, v84
	v_add_f32_e32 v82, v91, v82
	v_add_f32_e32 v88, v85, v82
	global_store_dwordx4 v[86:87], v[72:75], off
	v_lshlrev_b32_e32 v82, 16, v76
	v_and_b32_e32 v83, 0xffff0000, v76
	v_lshlrev_b32_e32 v76, 16, v77
	v_and_b32_e32 v77, 0xffff0000, v77
	v_lshlrev_b32_e32 v84, 16, v78
	v_and_b32_e32 v85, 0xffff0000, v78
	v_lshlrev_b32_e32 v78, 16, v79
	v_and_b32_e32 v79, 0xffff0000, v79
	v_pk_add_f32 v[70:71], v[70:71], v[76:77]
	v_pk_add_f32 v[68:69], v[68:69], v[82:83]
	v_pk_add_f32 v[76:77], v[66:67], v[78:79]
	v_pk_add_f32 v[78:79], v[64:65], v[84:85]
	v_mul_f32_e32 v64, v69, v69
	v_mul_f32_e32 v65, v71, v71
	v_mul_f32_e32 v66, v79, v79
	v_fmac_f32_e32 v64, v68, v68
	v_fmac_f32_e32 v65, v70, v70
	v_mul_f32_e32 v67, v77, v77
	v_fmac_f32_e32 v66, v78, v78
	v_add_f32_e32 v64, v64, v65
	v_add_f32_e32 v64, v66, v64
	v_fmac_f32_e32 v67, v76, v76
	v_add_f32_e32 v64, v67, v64
	v_add_f32_e32 v64, v88, v64
	v_mov_b32_e32 v65, v64
	v_mov_b32_e32 v154, v64
	s_nop 1
	v_permlane16_swap_b32_e32 v65, v154
	v_cvt_pk_bf16_f32 v66, v68, v69
	v_cvt_pk_bf16_f32 v67, v70, v71
	v_cvt_pk_bf16_f32 v68, v78, v79
	v_cvt_pk_bf16_f32 v69, v76, v77
	s_waitcnt lgkmcnt(0)
	v_add_f32_e32 v64, v65, v154
	v_mov_b32_e32 v65, v64
	v_mov_b32_e32 v154, v64
	s_nop 1
	v_permlane32_swap_b32_e32 v65, v154
	global_store_dwordx4 v[86:87], v[66:69], off offset:256
	s_and_saveexec_b64 s[14:15], s[6:7]
	s_cbranch_execz .LBB0_1151
	v_lshlrev_b64 v[66:67], 6, v[80:81]
	v_lshl_add_u64 v[66:67], s[20:21], 0, v[66:67]
	v_lshl_add_u64 v[66:67], s[12:13], 2, v[66:67]
	s_lshl_b32 s16, s28, 2
	s_mov_b32 s17, s36
	v_lshl_add_u64 v[66:67], v[66:67], 0, s[16:17]
	s_waitcnt lgkmcnt(0)
	v_add_f32_e32 v64, v65, v154
	global_store_dword v[66:67], v64, off
.LBB0_1151:
	s_or_b64 exec, exec, s[14:15]
	v_add_u32_e32 v64, 0x80, v130
	s_waitcnt lgkmcnt(0)
	v_ashrrev_i32_e32 v65, 31, v64
	v_lshlrev_b64 v[66:67], 11, v[64:65]
	v_lshl_add_u64 v[66:67], s[22:23], 0, v[66:67]
	v_lshl_add_u64 v[70:71], v[128:129], 1, v[66:67]
	s_waitcnt vmcnt(14)
	v_mov_b32_e32 v66, v202
	v_mov_b32_e32 v67, v203
	v_mov_b32_e32 v68, v204
	v_mov_b32_e32 v69, v205
	v_lshlrev_b32_e32 v72, 16, v66
	v_and_b32_e32 v73, 0xffff0000, v66
	v_lshlrev_b32_e32 v66, 16, v67
	v_and_b32_e32 v67, 0xffff0000, v67
	v_lshlrev_b32_e32 v74, 16, v68
	v_and_b32_e32 v75, 0xffff0000, v68
	v_lshlrev_b32_e32 v68, 16, v69
	v_and_b32_e32 v69, 0xffff0000, v69
	v_pk_add_f32 v[66:67], v[62:63], v[66:67]
	v_pk_add_f32 v[72:73], v[60:61], v[72:73]
	v_pk_add_f32 v[68:69], v[58:59], v[68:69]
	v_pk_add_f32 v[74:75], v[56:57], v[74:75]
	v_cvt_pk_bf16_f32 v56, v72, v73
	v_cvt_pk_bf16_f32 v57, v66, v67
	v_mul_f32_e32 v73, v73, v73
	v_cvt_pk_bf16_f32 v58, v74, v75
	v_cvt_pk_bf16_f32 v59, v68, v69
	v_mov_b32_e32 v60, v214
	v_mov_b32_e32 v61, v215
	v_mov_b32_e32 v62, v216
	v_mov_b32_e32 v63, v217
	v_mul_f32_e32 v67, v67, v67
	v_mul_f32_e32 v75, v75, v75
	v_fmac_f32_e32 v73, v72, v72
	v_fmac_f32_e32 v67, v66, v66
	v_mul_f32_e32 v69, v69, v69
	v_fmac_f32_e32 v75, v74, v74
	v_add_f32_e32 v66, v73, v67
	v_fmac_f32_e32 v69, v68, v68
	v_add_f32_e32 v66, v75, v66
	v_add_f32_e32 v72, v69, v66
	global_store_dwordx4 v[70:71], v[56:59], off
	v_lshlrev_b32_e32 v66, 16, v60
	v_and_b32_e32 v67, 0xffff0000, v60
	v_lshlrev_b32_e32 v60, 16, v61
	v_and_b32_e32 v61, 0xffff0000, v61
	v_lshlrev_b32_e32 v68, 16, v62
	v_and_b32_e32 v69, 0xffff0000, v62
	v_lshlrev_b32_e32 v62, 16, v63
	v_and_b32_e32 v63, 0xffff0000, v63
	v_pk_add_f32 v[54:55], v[54:55], v[60:61]
	v_pk_add_f32 v[52:53], v[52:53], v[66:67]
	v_pk_add_f32 v[60:61], v[50:51], v[62:63]
	v_pk_add_f32 v[62:63], v[48:49], v[68:69]
	v_mul_f32_e32 v48, v53, v53
	v_mul_f32_e32 v49, v55, v55
	v_mul_f32_e32 v50, v63, v63
	v_fmac_f32_e32 v48, v52, v52
	v_fmac_f32_e32 v49, v54, v54
	v_mul_f32_e32 v51, v61, v61
	v_fmac_f32_e32 v50, v62, v62
	v_add_f32_e32 v48, v48, v49
	v_add_f32_e32 v48, v50, v48
	v_fmac_f32_e32 v51, v60, v60
	v_add_f32_e32 v48, v51, v48
	v_add_f32_e32 v48, v72, v48
	v_mov_b32_e32 v49, v48
	v_mov_b32_e32 v154, v48
	s_nop 1
	v_permlane16_swap_b32_e32 v49, v154
	v_cvt_pk_bf16_f32 v50, v52, v53
	v_cvt_pk_bf16_f32 v51, v54, v55
	v_cvt_pk_bf16_f32 v52, v62, v63
	v_cvt_pk_bf16_f32 v53, v60, v61
	s_waitcnt lgkmcnt(0)
	v_add_f32_e32 v48, v49, v154
	v_mov_b32_e32 v49, v48
	v_mov_b32_e32 v154, v48
	s_nop 1
	v_permlane32_swap_b32_e32 v49, v154
	global_store_dwordx4 v[70:71], v[50:53], off offset:256
	s_and_saveexec_b64 s[14:15], s[6:7]
	s_cbranch_execz .LBB0_1153
	v_lshlrev_b64 v[50:51], 6, v[64:65]
	v_lshl_add_u64 v[50:51], s[20:21], 0, v[50:51]
	v_lshl_add_u64 v[50:51], s[12:13], 2, v[50:51]
	s_lshl_b32 s16, s28, 2
	s_mov_b32 s17, s36
	v_lshl_add_u64 v[50:51], v[50:51], 0, s[16:17]
	s_waitcnt lgkmcnt(0)
	v_add_f32_e32 v48, v49, v154
	global_store_dword v[50:51], v48, off
; __device__ __forceinline__ unsigned cvt_pk_bf16(float lo, float hi) { unsigned r; asm volatile("v_cvt_pk_bf16_f32 %0, %1, %2" : "=v"(r) : "v"(lo), "v"(hi)); return r; }
; __device__ __forceinline__ void UNPACK8(const u32x4 q, float (&f)[8]) { f[0] = bflo(q.x); f[1] = bfhi(q.x); f[2] = bflo(q.y); f[3] = bfhi(q.y); f[4] = bflo(q.z); f[5] = bfhi(q.z); f[6] = bflo(q.w); f[7] = bfhi(q.w); }
; #define EPI_FOR_ROWS() _Pragma("unroll") for (int ai = 0; ai < 2; ++ai) _Pragma("unroll") for (int m = 0; m < 4; ++m)
;     __device__ __forceinline__ void operator()(const f32x4 (&acc)[2][2][4][2], const Unit& u, int wr, int wc, int fr, int fq) const {
;     ...
;         EPI_FOR_ROWS() {
;             const int row = row0 + ai * 128 + m * 16; float ss = 0.f;
; #pragma unroll
;             for (int bj = 0; bj < 2; ++bj) { const int col = col0 + bj * 128; const size_t off = (size_t)row * 1024 + col;
;                 const u32x4 xw = *(const u32x4*)(xb + off); float xo[8]; UNPACK8(xw, xo);
;                 const f32x4 x0 = (f32x4){xo[0], xo[1], xo[2], xo[3]} + acc[ai][bj][m][0], x1 = (f32x4){xo[4], xo[5], xo[6], xo[7]} + acc[ai][bj][m][1];
;                 ss += (x0[0] * x0[0] + x0[1] * x0[1]) + (x0[2] * x0[2] + x0[3] * x0[3]) + (x1[0] * x1[0] + x1[1] * x1[1]) + (x1[2] * x1[2] + x1[3] * x1[3]);
;                 u32x4 w; w.x = cvt_pk_bf16(x0[0], x0[1]); w.y = cvt_pk_bf16(x0[2], x0[3]); w.z = cvt_pk_bf16(x1[0], x1[1]); w.w = cvt_pk_bf16(x1[2], x1[3]);
;                 *(u32x4*)(xb + off) = w; }
;             ss += __shfl_xor(ss, 16); ss += __shfl_xor(ss, 32);
;             if (fq == 0) ssq[(size_t)row * 16 + u.pn * 4 + wc] = ss;
.LBB0_1153:
	s_or_b64 exec, exec, s[14:15]
	v_add_u32_e32 v48, 0x90, v130
	s_waitcnt lgkmcnt(0)
	v_ashrrev_i32_e32 v49, 31, v48
	v_lshlrev_b64 v[50:51], 11, v[48:49]
	v_lshl_add_u64 v[50:51], s[22:23], 0, v[50:51]
	v_lshl_add_u64 v[54:55], v[128:129], 1, v[50:51]
	s_waitcnt vmcnt(14)
	v_mov_b32_e32 v50, v218
	v_mov_b32_e32 v51, v219
	v_mov_b32_e32 v52, v220
	v_mov_b32_e32 v53, v221
	v_lshlrev_b32_e32 v56, 16, v50
	v_and_b32_e32 v57, 0xffff0000, v50
	v_lshlrev_b32_e32 v50, 16, v51
	v_and_b32_e32 v51, 0xffff0000, v51
	v_lshlrev_b32_e32 v58, 16, v52
	v_and_b32_e32 v59, 0xffff0000, v52
	v_lshlrev_b32_e32 v52, 16, v53
	v_and_b32_e32 v53, 0xffff0000, v53
	v_pk_add_f32 v[50:51], v[46:47], v[50:51]
	v_pk_add_f32 v[56:57], v[44:45], v[56:57]
	v_pk_add_f32 v[52:53], v[42:43], v[52:53]
	v_pk_add_f32 v[58:59], v[40:41], v[58:59]
	v_cvt_pk_bf16_f32 v40, v56, v57
	v_cvt_pk_bf16_f32 v41, v50, v51
	v_mul_f32_e32 v57, v57, v57
	v_cvt_pk_bf16_f32 v42, v58, v59
	v_cvt_pk_bf16_f32 v43, v52, v53
	v_mov_b32_e32 v44, v222
	v_mov_b32_e32 v45, v223
	v_mov_b32_e32 v46, v224
	v_mov_b32_e32 v47, v225
	v_mul_f32_e32 v51, v51, v51
	v_mul_f32_e32 v59, v59, v59
	v_fmac_f32_e32 v57, v56, v56
	v_fmac_f32_e32 v51, v50, v50
	v_mul_f32_e32 v53, v53, v53
	v_fmac_f32_e32 v59, v58, v58
	v_add_f32_e32 v50, v57, v51
	v_fmac_f32_e32 v53, v52, v52
	v_add_f32_e32 v50, v59, v50
	v_add_f32_e32 v56, v53, v50
	global_store_dwordx4 v[54:55], v[40:43], off
	v_lshlrev_b32_e32 v50, 16, v44
	v_and_b32_e32 v51, 0xffff0000, v44
	v_lshlrev_b32_e32 v44, 16, v45
	v_and_b32_e32 v45, 0xffff0000, v45
	v_lshlrev_b32_e32 v52, 16, v46
	v_and_b32_e32 v53, 0xffff0000, v46
	v_lshlrev_b32_e32 v46, 16, v47
	v_and_b32_e32 v47, 0xffff0000, v47
	v_pk_add_f32 v[38:39], v[38:39], v[44:45]
	v_pk_add_f32 v[36:37], v[36:37], v[50:51]
	v_pk_add_f32 v[44:45], v[34:35], v[46:47]
	v_pk_add_f32 v[46:47], v[32:33], v[52:53]
	v_mul_f32_e32 v32, v37, v37
	v_mul_f32_e32 v33, v39, v39
	v_mul_f32_e32 v34, v47, v47
	v_fmac_f32_e32 v32, v36, v36
	v_fmac_f32_e32 v33, v38, v38
	v_mul_f32_e32 v35, v45, v45
	v_fmac_f32_e32 v34, v46, v46
	v_add_f32_e32 v32, v32, v33
	v_add_f32_e32 v32, v34, v32
	v_fmac_f32_e32 v35, v44, v44
	v_add_f32_e32 v32, v35, v32
	v_add_f32_e32 v32, v56, v32
	v_mov_b32_e32 v33, v32
	v_mov_b32_e32 v154, v32
	s_nop 1
	v_permlane16_swap_b32_e32 v33, v154
	v_cvt_pk_bf16_f32 v34, v36, v37
	v_cvt_pk_bf16_f32 v35, v38, v39
	v_cvt_pk_bf16_f32 v36, v46, v47
	v_cvt_pk_bf16_f32 v37, v44, v45
	s_waitcnt lgkmcnt(0)
	v_add_f32_e32 v32, v33, v154
	v_mov_b32_e32 v33, v32
	v_mov_b32_e32 v154, v32
	s_nop 1
	v_permlane32_swap_b32_e32 v33, v154
	global_store_dwordx4 v[54:55], v[34:37], off offset:256
	s_and_saveexec_b64 s[14:15], s[6:7]
	s_cbranch_execz .LBB0_1155
	v_lshlrev_b64 v[34:35], 6, v[48:49]
	v_lshl_add_u64 v[34:35], s[20:21], 0, v[34:35]
	v_lshl_add_u64 v[34:35], s[12:13], 2, v[34:35]
	s_lshl_b32 s16, s28, 2
	s_mov_b32 s17, s36
	v_lshl_add_u64 v[34:35], v[34:35], 0, s[16:17]
	s_waitcnt lgkmcnt(0)
	v_add_f32_e32 v32, v33, v154
	global_store_dword v[34:35], v32, off
; __device__ __forceinline__ unsigned cvt_pk_bf16(float lo, float hi) { unsigned r; asm volatile("v_cvt_pk_bf16_f32 %0, %1, %2" : "=v"(r) : "v"(lo), "v"(hi)); return r; }
; __device__ __forceinline__ void UNPACK8(const u32x4 q, float (&f)[8]) { f[0] = bflo(q.x); f[1] = bfhi(q.x); f[2] = bflo(q.y); f[3] = bfhi(q.y); f[4] = bflo(q.z); f[5] = bfhi(q.z); f[6] = bflo(q.w); f[7] = bfhi(q.w); }
; #define EPI_FOR_ROWS() _Pragma("unroll") for (int ai = 0; ai < 2; ++ai) _Pragma("unroll") for (int m = 0; m < 4; ++m)
;     __device__ __forceinline__ void operator()(const f32x4 (&acc)[2][2][4][2], const Unit& u, int wr, int wc, int fr, int fq) const {
;     ...
;         EPI_FOR_ROWS() {
;             const int row = row0 + ai * 128 + m * 16; float ss = 0.f;
; #pragma unroll
;             for (int bj = 0; bj < 2; ++bj) { const int col = col0 + bj * 128; const size_t off = (size_t)row * 1024 + col;
;                 const u32x4 xw = *(const u32x4*)(xb + off); float xo[8]; UNPACK8(xw, xo);
;                 const f32x4 x0 = (f32x4){xo[0], xo[1], xo[2], xo[3]} + acc[ai][bj][m][0], x1 = (f32x4){xo[4], xo[5], xo[6], xo[7]} + acc[ai][bj][m][1];
;                 ss += (x0[0] * x0[0] + x0[1] * x0[1]) + (x0[2] * x0[2] + x0[3] * x0[3]) + (x1[0] * x1[0] + x1[1] * x1[1]) + (x1[2] * x1[2] + x1[3] * x1[3]);
;                 u32x4 w; w.x = cvt_pk_bf16(x0[0], x0[1]); w.y = cvt_pk_bf16(x0[2], x0[3]); w.z = cvt_pk_bf16(x1[0], x1[1]); w.w = cvt_pk_bf16(x1[2], x1[3]);
;                 *(u32x4*)(xb + off) = w; }
;             ss += __shfl_xor(ss, 16); ss += __shfl_xor(ss, 32);
;             if (fq == 0) ssq[(size_t)row * 16 + u.pn * 4 + wc] = ss;
.LBB0_1155:
	s_or_b64 exec, exec, s[14:15]
	v_add_u32_e32 v32, 0xa0, v130
	s_waitcnt lgkmcnt(0)
	v_ashrrev_i32_e32 v33, 31, v32
	v_lshlrev_b64 v[34:35], 11, v[32:33]
	v_lshl_add_u64 v[34:35], s[22:23], 0, v[34:35]
	v_lshl_add_u64 v[38:39], v[128:129], 1, v[34:35]
	s_waitcnt vmcnt(14)
	v_mov_b32_e32 v34, v226
	v_mov_b32_e32 v35, v227
	v_mov_b32_e32 v36, v228
	v_mov_b32_e32 v37, v229
	v_lshlrev_b32_e32 v40, 16, v34
	v_and_b32_e32 v41, 0xffff0000, v34
	v_lshlrev_b32_e32 v34, 16, v35
	v_and_b32_e32 v35, 0xffff0000, v35
	v_lshlrev_b32_e32 v42, 16, v36
	v_and_b32_e32 v43, 0xffff0000, v36
	v_lshlrev_b32_e32 v36, 16, v37
	v_and_b32_e32 v37, 0xffff0000, v37
	v_pk_add_f32 v[34:35], v[30:31], v[34:35]
	v_pk_add_f32 v[40:41], v[28:29], v[40:41]
	v_pk_add_f32 v[36:37], v[26:27], v[36:37]
	v_pk_add_f32 v[42:43], v[24:25], v[42:43]
	v_cvt_pk_bf16_f32 v24, v40, v41
	v_cvt_pk_bf16_f32 v25, v34, v35
	v_mul_f32_e32 v41, v41, v41
	v_cvt_pk_bf16_f32 v26, v42, v43
	v_cvt_pk_bf16_f32 v27, v36, v37
	v_mov_b32_e32 v28, v230
	v_mov_b32_e32 v29, v231
	v_mov_b32_e32 v30, v232
	v_mov_b32_e32 v31, v233
	v_mul_f32_e32 v35, v35, v35
	v_mul_f32_e32 v43, v43, v43
	v_fmac_f32_e32 v41, v40, v40
	v_fmac_f32_e32 v35, v34, v34
	v_mul_f32_e32 v37, v37, v37
	v_fmac_f32_e32 v43, v42, v42
	v_add_f32_e32 v34, v41, v35
	v_fmac_f32_e32 v37, v36, v36
	v_add_f32_e32 v34, v43, v34
	v_add_f32_e32 v40, v37, v34
	global_store_dwordx4 v[38:39], v[24:27], off
	v_lshlrev_b32_e32 v34, 16, v28
	v_and_b32_e32 v35, 0xffff0000, v28
	v_lshlrev_b32_e32 v28, 16, v29
	v_and_b32_e32 v29, 0xffff0000, v29
	v_lshlrev_b32_e32 v36, 16, v30
	v_and_b32_e32 v37, 0xffff0000, v30
	v_lshlrev_b32_e32 v30, 16, v31
	v_and_b32_e32 v31, 0xffff0000, v31
	v_pk_add_f32 v[22:23], v[22:23], v[28:29]
	v_pk_add_f32 v[20:21], v[20:21], v[34:35]
	v_pk_add_f32 v[28:29], v[18:19], v[30:31]
	v_pk_add_f32 v[30:31], v[16:17], v[36:37]
	v_mul_f32_e32 v16, v21, v21
	v_mul_f32_e32 v17, v23, v23
	v_mul_f32_e32 v18, v31, v31
	v_fmac_f32_e32 v16, v20, v20
	v_fmac_f32_e32 v17, v22, v22
	v_mul_f32_e32 v19, v29, v29
	v_fmac_f32_e32 v18, v30, v30
	v_add_f32_e32 v16, v16, v17
	v_add_f32_e32 v16, v18, v16
	v_fmac_f32_e32 v19, v28, v28
	v_add_f32_e32 v16, v19, v16
	v_add_f32_e32 v16, v40, v16
	v_mov_b32_e32 v17, v16
	v_mov_b32_e32 v154, v16
	s_nop 1
	v_permlane16_swap_b32_e32 v17, v154
	v_cvt_pk_bf16_f32 v18, v20, v21
	v_cvt_pk_bf16_f32 v19, v22, v23
	v_cvt_pk_bf16_f32 v20, v30, v31
	v_cvt_pk_bf16_f32 v21, v28, v29
	s_waitcnt lgkmcnt(0)
	v_add_f32_e32 v16, v17, v154
	v_mov_b32_e32 v17, v16
	v_mov_b32_e32 v154, v16
	s_nop 1
	v_permlane32_swap_b32_e32 v17, v154
	global_store_dwordx4 v[38:39], v[18:21], off offset:256
	s_and_saveexec_b64 s[14:15], s[6:7]
	s_cbranch_execz .LBB0_1157
	v_lshlrev_b64 v[18:19], 6, v[32:33]
	v_lshl_add_u64 v[18:19], s[20:21], 0, v[18:19]
	v_lshl_add_u64 v[18:19], s[12:13], 2, v[18:19]
	s_lshl_b32 s16, s28, 2
	s_mov_b32 s17, s36
	v_lshl_add_u64 v[18:19], v[18:19], 0, s[16:17]
	s_waitcnt lgkmcnt(0)
	v_add_f32_e32 v16, v17, v154
	global_store_dword v[18:19], v16, off
.LBB0_1157:
	s_or_b64 exec, exec, s[14:15]
	v_add_u32_e32 v16, 0xb0, v130
	s_waitcnt lgkmcnt(0)
	v_ashrrev_i32_e32 v17, 31, v16
	v_lshlrev_b64 v[18:19], 11, v[16:17]
	v_lshl_add_u64 v[18:19], s[22:23], 0, v[18:19]
	v_lshl_add_u64 v[22:23], v[128:129], 1, v[18:19]
	s_waitcnt vmcnt(14)
	v_mov_b32_e32 v18, v234
	v_mov_b32_e32 v19, v235
	v_mov_b32_e32 v20, v236
	v_mov_b32_e32 v21, v237
	v_lshlrev_b32_e32 v24, 16, v18
	v_and_b32_e32 v25, 0xffff0000, v18
	v_lshlrev_b32_e32 v18, 16, v19
	v_and_b32_e32 v19, 0xffff0000, v19
	v_lshlrev_b32_e32 v26, 16, v20
	v_and_b32_e32 v27, 0xffff0000, v20
	v_lshlrev_b32_e32 v20, 16, v21
	v_and_b32_e32 v21, 0xffff0000, v21
	v_pk_add_f32 v[18:19], v[14:15], v[18:19]
	v_pk_add_f32 v[24:25], v[12:13], v[24:25]
	v_pk_add_f32 v[20:21], v[10:11], v[20:21]
	v_pk_add_f32 v[26:27], v[8:9], v[26:27]
	v_cvt_pk_bf16_f32 v8, v24, v25
	v_cvt_pk_bf16_f32 v9, v18, v19
	v_mul_f32_e32 v25, v25, v25
	v_cvt_pk_bf16_f32 v10, v26, v27
	v_cvt_pk_bf16_f32 v11, v20, v21
	v_mov_b32_e32 v12, v238
	v_mov_b32_e32 v13, v239
	v_mov_b32_e32 v14, v240
	v_mov_b32_e32 v15, v241
	v_mul_f32_e32 v19, v19, v19
	v_mul_f32_e32 v27, v27, v27
	v_fmac_f32_e32 v25, v24, v24
	v_fmac_f32_e32 v19, v18, v18
	v_mul_f32_e32 v21, v21, v21
	v_fmac_f32_e32 v27, v26, v26
	v_add_f32_e32 v18, v25, v19
	v_fmac_f32_e32 v21, v20, v20
	v_add_f32_e32 v18, v27, v18
	v_add_f32_e32 v24, v21, v18
	global_store_dwordx4 v[22:23], v[8:11], off
	v_lshlrev_b32_e32 v18, 16, v12
	v_and_b32_e32 v19, 0xffff0000, v12
	v_lshlrev_b32_e32 v12, 16, v13
	v_and_b32_e32 v13, 0xffff0000, v13
	v_lshlrev_b32_e32 v20, 16, v14
	v_and_b32_e32 v21, 0xffff0000, v14
	v_lshlrev_b32_e32 v14, 16, v15
	v_and_b32_e32 v15, 0xffff0000, v15
	v_pk_add_f32 v[6:7], v[6:7], v[12:13]
	v_pk_add_f32 v[4:5], v[4:5], v[18:19]
	v_pk_add_f32 v[12:13], v[2:3], v[14:15]
	v_pk_add_f32 v[14:15], v[0:1], v[20:21]
	v_mul_f32_e32 v0, v5, v5
	v_mul_f32_e32 v1, v7, v7
	v_mul_f32_e32 v2, v15, v15
	v_fmac_f32_e32 v0, v4, v4
	v_fmac_f32_e32 v1, v6, v6
	v_mul_f32_e32 v3, v13, v13
	v_fmac_f32_e32 v2, v14, v14
	v_add_f32_e32 v0, v0, v1
	v_add_f32_e32 v0, v2, v0
	v_fmac_f32_e32 v3, v12, v12
	v_add_f32_e32 v0, v3, v0
	v_add_f32_e32 v0, v24, v0
	v_mov_b32_e32 v1, v0
	v_mov_b32_e32 v154, v0
	s_nop 1
	v_permlane16_swap_b32_e32 v1, v154
	v_cvt_pk_bf16_f32 v2, v4, v5
	v_cvt_pk_bf16_f32 v3, v6, v7
	v_cvt_pk_bf16_f32 v4, v14, v15
	v_cvt_pk_bf16_f32 v5, v12, v13
	s_waitcnt lgkmcnt(0)
	v_add_f32_e32 v0, v1, v154
	v_mov_b32_e32 v1, v0
	v_mov_b32_e32 v154, v0
	s_nop 1
	v_permlane32_swap_b32_e32 v1, v154
	global_store_dwordx4 v[22:23], v[2:5], off offset:256
	s_and_saveexec_b64 s[14:15], s[6:7]
	s_cbranch_execz .LBB0_1159
	v_lshlrev_b64 v[2:3], 6, v[16:17]
	v_lshl_add_u64 v[2:3], s[20:21], 0, v[2:3]
	v_lshl_add_u64 v[2:3], s[12:13], 2, v[2:3]
	s_lshl_b32 s12, s28, 2
	s_mov_b32 s13, s36
	v_lshl_add_u64 v[2:3], v[2:3], 0, s[12:13]
	s_waitcnt lgkmcnt(0)
	v_add_f32_e32 v0, v1, v154
	global_store_dword v[2:3], v0, off
